# scan LDS-DMA split: the QN and VT images of stage n+2 are issued in the middle of step n behind a new mid-step barrier (their slots are dead after phase B), the rest of a stage at the start of the ste
# speedup vs baseline: 1.0116x; 1.0116x over previous
.LBB0_775:
	v_mov_b32_e32 v98, v1
	s_and_b32 s3, s1, 1
	v_ashrrev_i32_e32 v162, 5, v98
	v_and_b32_e32 v66, 31, v98
	v_and_b32_e32 v67, 0xffffffe0, v98
	v_lshlrev_b32_e32 v68, 2, v162
	s_mul_i32 s4, s3, 0xf400
	v_xad_u32 v69, v68, v66, v67
	v_add_u32_e32 v68, 8, v68
	s_add_i32 s4, s4, 0
	v_xad_u32 v67, v68, v66, v67
	v_lshl_add_u32 v138, v69, 4, s4
	v_or_b32_e32 v163, s0, v66
	v_lshl_add_u32 v142, v67, 4, s4
	ds_read_b128 v[66:69], v138
	ds_read_b128 v[70:73], v138 offset:2048
	ds_read_b128 v[74:77], v142 offset:1024
	ds_read_b128 v[78:81], v142 offset:3072
	ds_read_b128 v[82:85], v138 offset:4096
	ds_read_b128 v[86:89], v138 offset:6144
	ds_read_b128 v[90:93], v142 offset:5120
	ds_read_b128 v[94:97], v142 offset:7168
	v_lshlrev_b32_e32 v99, 4, v163
	v_lshlrev_b32_e32 v100, 3, v162
	v_mov_b32_e32 v164, s4
	v_cvt_pk_bf16_f32 v126, v2, v3
	v_cvt_pk_bf16_f32 v127, v4, v5
	v_cvt_pk_bf16_f32 v128, v6, v7
	v_cvt_pk_bf16_f32 v129, v8, v9
	v_cvt_pk_bf16_f32 v114, v18, v19
	v_cvt_pk_bf16_f32 v115, v20, v21
	v_cvt_pk_bf16_f32 v116, v22, v23
	v_cvt_pk_bf16_f32 v117, v24, v25
	v_cvt_pk_bf16_f32 v118, v26, v27
	v_cvt_pk_bf16_f32 v119, v28, v29
	v_cvt_pk_bf16_f32 v120, v30, v31
	v_cvt_pk_bf16_f32 v121, v32, v33
	v_cvt_pk_bf16_f32 v122, v34, v35
	v_cvt_pk_bf16_f32 v123, v36, v37
	v_cvt_pk_bf16_f32 v124, v38, v39
	v_cvt_pk_bf16_f32 v125, v40, v41
	v_cvt_pk_bf16_f32 v146, v42, v43
	v_cvt_pk_bf16_f32 v147, v44, v45
	v_cvt_pk_bf16_f32 v148, v46, v47
	v_cvt_pk_bf16_f32 v149, v48, v49
	v_cvt_pk_bf16_f32 v150, v50, v51
	v_cvt_pk_bf16_f32 v151, v52, v53
	v_cvt_pk_bf16_f32 v152, v54, v55
	v_cvt_pk_bf16_f32 v153, v56, v57
	v_cvt_pk_bf16_f32 v154, v58, v59
	v_cvt_pk_bf16_f32 v155, v60, v61
	v_cvt_pk_bf16_f32 v156, v62, v63
	v_cvt_pk_bf16_f32 v157, v64, v65
	v_add3_u32 v218, s4, v99, v100
	ds_read_b128 v[130:133], v138 offset:8192
	v_lshl_add_u32 v165, v162, 4, s4
	v_lshl_add_u32 v222, v98, 4, s4
	v_cvt_pk_bf16_f32 v158, v10, v11
	v_cvt_pk_bf16_f32 v159, v12, v13
	v_cvt_pk_bf16_f32 v160, v14, v15
	s_waitcnt lgkmcnt(8)
	v_mfma_f32_32x32x16_bf16 v[98:113], v[66:69], v[126:129], 0
	v_cvt_pk_bf16_f32 v161, v16, v17
	ds_read_b128 v[66:69], v142 offset:9216
	s_waitcnt lgkmcnt(7)
	v_mfma_f32_32x32x16_bf16 v[98:113], v[74:77], v[158:161], v[98:113]
	ds_read_b128 v[74:77], v138 offset:10240
	v_mfma_f32_32x32x16_bf16 v[98:113], v[70:73], v[114:117], v[98:113]
	ds_read_b128 v[70:73], v142 offset:11264
	s_waitcnt lgkmcnt(8)
	v_mfma_f32_32x32x16_bf16 v[98:113], v[78:81], v[118:121], v[98:113]
	ds_read_b128 v[78:81], v138 offset:12288
	s_waitcnt lgkmcnt(8)
	v_mfma_f32_32x32x16_bf16 v[98:113], v[82:85], v[122:125], v[98:113]
	ds_read_b128 v[134:137], v142 offset:13312
	s_waitcnt lgkmcnt(7)
	v_mfma_f32_32x32x16_bf16 v[98:113], v[90:93], v[146:149], v[98:113]
	ds_read_b128 v[138:141], v138 offset:14336
	v_mfma_f32_32x32x16_bf16 v[98:113], v[86:89], v[150:153], v[98:113]
	ds_read_b128 v[142:145], v142 offset:15360
	s_waitcnt lgkmcnt(8)
	v_mfma_f32_32x32x16_bf16 v[98:113], v[94:97], v[154:157], v[98:113]
	ds_read_b128 v[166:169], v222 offset:16384
	s_waitcnt lgkmcnt(8)
	v_mfma_f32_32x32x16_bf16 v[82:97], v[130:133], v[126:129], 0
	ds_read_b128 v[130:133], v222 offset:17408
	s_waitcnt lgkmcnt(8)
	v_mfma_f32_32x32x16_bf16 v[82:97], v[66:69], v[158:161], v[82:97]
	ds_read_b128 v[170:173], v222 offset:18432
	s_waitcnt lgkmcnt(8)
	v_mfma_f32_32x32x16_bf16 v[82:97], v[74:77], v[114:117], v[82:97]
	ds_read_b128 v[174:177], v222 offset:19456
	s_waitcnt lgkmcnt(8)
	v_mfma_f32_32x32x16_bf16 v[82:97], v[70:73], v[118:121], v[82:97]
	ds_read_b128 v[178:181], v222 offset:20480
	ds_read_b128 v[182:185], v165 offset:61440
	ds_read_b64 v[206:207], v218 offset:45056
	s_waitcnt lgkmcnt(10)
	v_mfma_f32_32x32x16_bf16 v[82:97], v[78:81], v[122:125], v[82:97]
	ds_read_b128 v[186:189], v222 offset:21504
	ds_read_b128 v[190:193], v165 offset:61472
	ds_read_b64 v[208:209], v218 offset:47104
	s_waitcnt lgkmcnt(12)
	v_mfma_f32_32x32x16_bf16 v[82:97], v[134:137], v[146:149], v[82:97]
	ds_read_b128 v[134:137], v222 offset:22528
	ds_read_b128 v[194:197], v165 offset:61504
	ds_read_b64 v[210:211], v218 offset:49152
	s_waitcnt lgkmcnt(14)
	v_mfma_f32_32x32x16_bf16 v[82:97], v[138:141], v[150:153], v[82:97]
	ds_read_b128 v[138:141], v222 offset:23552
	ds_read_b128 v[198:201], v165 offset:61536
	ds_read_b64 v[212:213], v218 offset:51200
	s_waitcnt lgkmcnt(14)
	v_mfma_f32_32x32x16_bf16 v[82:97], v[142:145], v[154:157], v[82:97]
	ds_read_b128 v[142:145], v222 offset:24576
	ds_read_b128 v[202:205], v165 offset:61568
	ds_read_b64 v[214:215], v218 offset:53248
	s_waitcnt lgkmcnt(12)
	v_lshlrev_b32_e32 v66, 16, v206
	v_and_b32_e32 v67, 0xffff0000, v206
	v_pk_fma_f32 v[182:183], v[98:99], v[182:183], v[66:67] neg_lo:[1,0,0] neg_hi:[1,0,0]
	v_lshlrev_b32_e32 v98, 16, v207
	v_and_b32_e32 v99, 0xffff0000, v207
	v_mfma_f32_32x32x16_bf16 v[66:81], v[166:169], v[126:129], 0
	v_fma_f32 v184, -v100, v184, v98
	v_fma_f32 v185, -v101, v185, v99
	ds_read_b128 v[98:101], v222 offset:25600
	ds_read_b128 v[166:169], v165 offset:61600
	ds_read_b64 v[206:207], v218 offset:55296
	s_waitcnt lgkmcnt(12)
	v_lshlrev_b32_e32 v216, 16, v208
	v_and_b32_e32 v217, 0xffff0000, v208
	v_pk_fma_f32 v[190:191], v[102:103], v[190:191], v[216:217] neg_lo:[1,0,0] neg_hi:[1,0,0]
	v_lshlrev_b32_e32 v102, 16, v209
	v_and_b32_e32 v103, 0xffff0000, v209
	v_mfma_f32_32x32x16_bf16 v[66:81], v[130:133], v[158:161], v[66:81]
	v_fma_f32 v192, -v104, v192, v102
	v_fma_f32 v193, -v105, v193, v103
	ds_read_b128 v[102:105], v222 offset:26624
	ds_read_b128 v[130:133], v165 offset:61632
	ds_read_b64 v[208:209], v218 offset:57344
	s_waitcnt lgkmcnt(12)
	v_lshlrev_b32_e32 v216, 16, v210
	v_and_b32_e32 v217, 0xffff0000, v210
	v_pk_fma_f32 v[194:195], v[106:107], v[194:195], v[216:217] neg_lo:[1,0,0] neg_hi:[1,0,0]
	v_lshlrev_b32_e32 v106, 16, v211
	v_and_b32_e32 v107, 0xffff0000, v211
	v_mfma_f32_32x32x16_bf16 v[66:81], v[170:173], v[114:117], v[66:81]
	v_fma_f32 v196, -v108, v196, v106
	v_fma_f32 v197, -v109, v197, v107
	ds_read_b128 v[106:109], v222 offset:27648
	ds_read_b128 v[170:173], v165 offset:61664
	ds_read_b64 v[210:211], v218 offset:59392
	s_waitcnt lgkmcnt(12)
	v_lshlrev_b32_e32 v216, 16, v212
	v_and_b32_e32 v217, 0xffff0000, v212
	v_pk_fma_f32 v[198:199], v[110:111], v[198:199], v[216:217] neg_lo:[1,0,0] neg_hi:[1,0,0]
	v_lshlrev_b32_e32 v110, 16, v213
	v_and_b32_e32 v111, 0xffff0000, v213
	v_mfma_f32_32x32x16_bf16 v[66:81], v[174:177], v[118:121], v[66:81]
	v_fma_f32 v200, -v112, v200, v110
	v_fma_f32 v201, -v113, v201, v111
	ds_read_b128 v[110:113], v222 offset:28672
	s_waitcnt lgkmcnt(10)
	v_lshlrev_b32_e32 v174, 16, v214
	v_and_b32_e32 v175, 0xffff0000, v214
	v_pk_fma_f32 v[202:203], v[82:83], v[202:203], v[174:175] neg_lo:[1,0,0] neg_hi:[1,0,0]
	v_lshlrev_b32_e32 v82, 16, v215
	v_and_b32_e32 v83, 0xffff0000, v215
	v_mfma_f32_32x32x16_bf16 v[66:81], v[178:181], v[122:125], v[66:81]
	v_fma_f32 v178, -v84, v204, v82
	v_fma_f32 v179, -v85, v205, v83
	ds_read_b128 v[82:85], v222 offset:29696
	s_waitcnt lgkmcnt(8)
	v_lshlrev_b32_e32 v174, 16, v206
	v_and_b32_e32 v175, 0xffff0000, v206
	v_pk_fma_f32 v[180:181], v[86:87], v[166:167], v[174:175] neg_lo:[1,0,0] neg_hi:[1,0,0]
	v_lshlrev_b32_e32 v86, 16, v207
	v_and_b32_e32 v87, 0xffff0000, v207
	v_mfma_f32_32x32x16_bf16 v[66:81], v[186:189], v[146:149], v[66:81]
	v_fma_f32 v186, -v88, v168, v86
	v_fma_f32 v187, -v89, v169, v87
	ds_read_b128 v[86:89], v222 offset:30720
	s_waitcnt lgkmcnt(6)
	v_lshlrev_b32_e32 v166, 16, v208
	v_and_b32_e32 v167, 0xffff0000, v208
	v_pk_fma_f32 v[188:189], v[90:91], v[130:131], v[166:167] neg_lo:[1,0,0] neg_hi:[1,0,0]
	v_lshlrev_b32_e32 v90, 16, v209
	v_and_b32_e32 v91, 0xffff0000, v209
	v_mfma_f32_32x32x16_bf16 v[66:81], v[134:137], v[150:153], v[66:81]
	v_fma_f32 v204, -v92, v132, v90
	v_fma_f32 v205, -v93, v133, v91
	ds_read_b128 v[90:93], v222 offset:31744
	s_waitcnt lgkmcnt(4)
	v_lshlrev_b32_e32 v130, 16, v210
	v_and_b32_e32 v131, 0xffff0000, v210
	v_pk_fma_f32 v[206:207], v[94:95], v[170:171], v[130:131] neg_lo:[1,0,0] neg_hi:[1,0,0]
	v_lshlrev_b32_e32 v94, 16, v211
	v_and_b32_e32 v95, 0xffff0000, v211
	v_mfma_f32_32x32x16_bf16 v[66:81], v[138:141], v[154:157], v[66:81]
	v_fma_f32 v208, -v96, v172, v94
	v_fma_f32 v209, -v97, v173, v95
	ds_read_b128 v[94:97], v222 offset:32768
	v_cvt_pk_bf16_f32 v166, v182, v183
	v_cvt_pk_bf16_f32 v167, v184, v185
	v_cvt_pk_bf16_f32 v168, v190, v191
	v_cvt_pk_bf16_f32 v169, v192, v193
	v_mfma_f32_32x32x16_bf16 v[130:145], v[142:145], v[126:129], 0
	ds_read_b128 v[170:173], v222 offset:33792
	v_cvt_pk_bf16_f32 v174, v194, v195
	v_cvt_pk_bf16_f32 v175, v196, v197
	v_cvt_pk_bf16_f32 v176, v198, v199
	v_cvt_pk_bf16_f32 v177, v200, v201
	v_mfma_f32_32x32x16_bf16 v[130:145], v[98:101], v[158:161], v[130:145]
	ds_read_b128 v[98:101], v222 offset:34816
	v_cvt_pk_bf16_f32 v158, v202, v203
	v_cvt_pk_bf16_f32 v159, v178, v179
	v_cvt_pk_bf16_f32 v160, v180, v181
	v_cvt_pk_bf16_f32 v161, v186, v187
	v_mfma_f32_32x32x16_bf16 v[130:145], v[102:105], v[114:117], v[130:145]
	ds_read_b128 v[178:181], v222 offset:35840
	v_cvt_pk_bf16_f32 v182, v188, v189
	v_cvt_pk_bf16_f32 v183, v204, v205
	v_cvt_pk_bf16_f32 v184, v206, v207
	v_cvt_pk_bf16_f32 v185, v208, v209
	v_mfma_f32_32x32x16_bf16 v[130:145], v[106:109], v[118:121], v[130:145]
	ds_read_b128 v[186:189], v222 offset:36864
	ds_read_b128 v[190:193], v165 offset:61440
	s_waitcnt lgkmcnt(9)
	v_mfma_f32_32x32x16_bf16 v[130:145], v[110:113], v[122:125], v[130:145]
	ds_read_b128 v[194:197], v222 offset:37888
	ds_read_b128 v[198:201], v165 offset:61472
	s_waitcnt lgkmcnt(10)
	v_mfma_f32_32x32x16_bf16 v[130:145], v[82:85], v[146:149], v[130:145]
	ds_read_b128 v[146:149], v165 offset:61504
	s_waitcnt lgkmcnt(10)
	v_mfma_f32_32x32x16_bf16 v[130:145], v[86:89], v[150:153], v[130:145]
	ds_read_b128 v[150:153], v165 offset:61536
	s_waitcnt lgkmcnt(10)
	v_mfma_f32_32x32x16_bf16 v[130:145], v[90:93], v[154:157], v[130:145]
	s_barrier
	ds_read_b128 v[154:157], v222 offset:38912
	ds_read_b128 v[202:205], v165 offset:61568
	s_waitcnt lgkmcnt(11)
	v_mfma_f32_32x32x16_bf16 v[114:129], v[94:97], v[166:169], 0
	ds_read_b128 v[206:209], v222 offset:39936
	ds_read_b128 v[210:213], v165 offset:61600
	s_waitcnt lgkmcnt(12)
	v_mfma_f32_32x32x16_bf16 v[114:129], v[170:173], v[174:177], v[114:129]
	ds_read_b128 v[170:173], v222 offset:40960
	ds_read_b128 v[214:217], v165 offset:61632
	s_waitcnt lgkmcnt(13)
	v_mfma_f32_32x32x16_bf16 v[98:113], v[98:101], v[166:169], 0
	ds_read_b128 v[166:169], v222 offset:41984
	ds_read_b128 v[218:221], v165 offset:61664
	s_waitcnt lgkmcnt(12)
	v_mul_f32_e64 v84, v68, v192
	v_mul_f32_e64 v85, v69, v193
	s_waitcnt lgkmcnt(10)
	v_pk_mul_f32 v[86:87], v[70:71], v[198:199]
	v_pk_mul_f32 v[88:89], v[72:73], v[200:201]
	s_waitcnt lgkmcnt(9)
	v_pk_mul_f32 v[90:91], v[74:75], v[146:147]
	v_mfma_f32_32x32x16_bf16 v[98:113], v[178:181], v[174:177], v[98:113]
	v_mul_f32_e64 v92, v76, v148
	v_mul_f32_e64 v93, v77, v149
	s_waitcnt lgkmcnt(8)
	v_mul_f32_e64 v94, v78, v150
	v_mul_f32_e64 v95, v79, v151
	v_pk_mul_f32 v[96:97], v[80:81], v[152:153]
	v_pk_mul_f32 v[82:83], v[66:67], v[190:191]
	ds_read_b128 v[146:149], v222 offset:43008
	v_mfma_f32_32x32x16_bf16 v[98:113], v[186:189], v[158:161], v[98:113]
	ds_read_b128 v[150:153], v222 offset:44032
	s_waitcnt lgkmcnt(8)
	v_mul_f32_e64 v68, v132, v204
	v_mul_f32_e64 v69, v133, v205
	s_waitcnt lgkmcnt(6)
	v_pk_mul_f32 v[70:71], v[134:135], v[210:211]
	v_pk_mul_f32 v[72:73], v[136:137], v[212:213]
	s_waitcnt lgkmcnt(4)
	v_pk_mul_f32 v[74:75], v[138:139], v[214:215]
	v_pk_mul_f32 v[76:77], v[140:141], v[216:217]
	v_mfma_f32_32x32x16_bf16 v[98:113], v[194:197], v[182:185], v[98:113]
	s_waitcnt lgkmcnt(2)
	v_mul_f32_e64 v78, v142, v218
	v_mul_f32_e64 v79, v143, v219
	v_mul_f32_e64 v80, v144, v220
	v_mul_f32_e64 v81, v145, v221
	v_pk_mul_f32 v[66:67], v[130:131], v[202:203]
	v_mov_b32_e32 v131, v1
	ds_read_b32 v130, v164 offset:61692
	v_cvt_pk_bf16_f32 v174, v114, v115
	v_lshrrev_b32_e32 v133, 2, v131
	v_ashrrev_i32_e32 v134, 3, v131
	v_and_b32_e32 v135, 1, v131
	v_bfe_u32 v132, v131, 4, 1
	v_bfi_b32 v133, -4, v134, v133
	v_lshlrev_b32_e32 v136, 2, v135
	v_lshlrev_b32_e32 v135, 5, v135
	v_add_u32_e32 v134, 8, v133
	v_lshl_or_b32 v136, v132, 3, v136
	v_lshl_or_b32 v132, v132, 6, v135
	v_xad_u32 v144, v136, v133, v132
	v_xad_u32 v145, v134, v136, v132
	ds_read_b128 v[132:135], v165 offset:61696
	ds_read_b128 v[136:139], v165 offset:61728
	ds_read_b128 v[140:143], v165 offset:61760
	ds_read_b128 v[158:161], v165 offset:61792
	v_lshlrev_b32_e32 v131, 2, v131
	v_and_b32_e32 v131, 8, v131
	v_lshl_or_b32 v144, v144, 4, v131
	v_lshl_or_b32 v131, v145, 4, v131
	v_cvt_pk_bf16_f32 v175, v116, v117
	v_cvt_pk_bf16_f32 v176, v118, v119
	v_cvt_pk_bf16_f32 v177, v120, v121
	v_cvt_pk_bf16_f32 v178, v122, v123
	v_cvt_pk_bf16_f32 v179, v124, v125
	v_cvt_pk_bf16_f32 v180, v126, v127
	v_cvt_pk_bf16_f32 v181, v128, v129
	v_cvt_pk_bf16_f32 v182, v98, v99
	v_cvt_pk_bf16_f32 v183, v100, v101
	v_cvt_pk_bf16_f32 v184, v102, v103
	v_cvt_pk_bf16_f32 v185, v104, v105
	v_mfma_f32_32x32x16_bf16 v[82:97], v[154:157], v[174:177], v[82:97]
	v_cvt_pk_bf16_f32 v154, v106, v107
	v_cvt_pk_bf16_f32 v155, v108, v109
	v_cvt_pk_bf16_f32 v156, v110, v111
	v_cvt_pk_bf16_f32 v157, v112, v113
	v_mfma_f32_32x32x16_bf16 v[82:97], v[206:209], v[178:181], v[82:97]
	v_add_u32_e32 v144, s4, v144
	v_add_u32_e32 v131, s4, v131
	ds_read_b64_tr_b16 v[186:187], v144
	ds_read_b64_tr_b16 v[188:189], v131
	ds_read_b128 v[190:193], v165 offset:61824
	ds_read_b128 v[194:197], v165 offset:61856
	s_waitcnt lgkmcnt(7)
	v_pk_mul_f32 v[114:115], v[114:115], v[132:133]
	v_pk_mul_f32 v[116:117], v[116:117], v[134:135]
	s_waitcnt lgkmcnt(6)
	v_pk_mul_f32 v[118:119], v[118:119], v[136:137]
	v_pk_mul_f32 v[120:121], v[120:121], v[138:139]
	v_mfma_f32_32x32x16_bf16 v[66:81], v[170:173], v[174:177], v[66:81]
	ds_read_b64_tr_b16 v[132:133], v144 offset:256
	ds_read_b64_tr_b16 v[134:135], v131 offset:256
	ds_read_b128 v[136:139], v165 offset:61888
	ds_read_b128 v[170:173], v165 offset:61920
	s_waitcnt lgkmcnt(9)
	v_pk_mul_f32 v[122:123], v[122:123], v[140:141]
	v_pk_mul_f32 v[124:125], v[124:125], v[142:143]
	s_waitcnt lgkmcnt(8)
	v_pk_mul_f32 v[126:127], v[126:127], v[158:159]
	v_pk_mul_f32 v[128:129], v[128:129], v[160:161]
	v_mfma_f32_32x32x16_bf16 v[66:81], v[166:169], v[178:181], v[66:81]
	v_cvt_pk_bf16_f32 v114, v114, v115
	v_cvt_pk_bf16_f32 v115, v116, v117
	v_cvt_pk_bf16_f32 v116, v118, v119
	v_cvt_pk_bf16_f32 v117, v120, v121
	v_cvt_pk_bf16_f32 v118, v122, v123
	v_cvt_pk_bf16_f32 v119, v124, v125
	v_cvt_pk_bf16_f32 v120, v126, v127
	v_cvt_pk_bf16_f32 v121, v128, v129
	ds_read_b64_tr_b16 v[122:123], v144 offset:8192
	ds_read_b64_tr_b16 v[124:125], v131 offset:8192
	s_waitcnt lgkmcnt(7)
	v_pk_mul_f32 v[98:99], v[98:99], v[190:191]
	v_pk_mul_f32 v[100:101], v[100:101], v[192:193]
	s_waitcnt lgkmcnt(6)
	v_pk_mul_f32 v[102:103], v[102:103], v[194:195]
	v_pk_mul_f32 v[104:105], v[104:105], v[196:197]
	v_mfma_f32_32x32x16_bf16 v[66:81], v[146:149], v[182:185], v[66:81]
	ds_read_b64_tr_b16 v[126:127], v144 offset:8448
	ds_read_b64_tr_b16 v[128:129], v131 offset:8448
	s_waitcnt lgkmcnt(5)
	v_mul_f32_e64 v106, v106, v136
	v_mul_f32_e64 v107, v107, v137
	v_pk_mul_f32 v[108:109], v[108:109], v[138:139]
	s_waitcnt lgkmcnt(4)
	v_pk_mul_f32 v[110:111], v[110:111], v[170:171]
	v_pk_mul_f32 v[112:113], v[112:113], v[172:173]
	v_mfma_f32_32x32x16_bf16 v[66:81], v[150:153], v[154:157], v[66:81]
	v_mul_f32_e64 v16, v16, v130
	v_mul_f32_e64 v17, v17, v130
	v_mul_f32_e64 v14, v14, v130
	v_mul_f32_e64 v15, v15, v130
	v_mul_f32_e64 v12, v12, v130
	v_mul_f32_e64 v13, v13, v130
	v_pk_mul_f32 v[10:11], v[10:11], v[130:131] op_sel_hi:[1,0]
	v_pk_mul_f32 v[8:9], v[8:9], v[130:131] op_sel_hi:[1,0]
	v_pk_mul_f32 v[6:7], v[6:7], v[130:131] op_sel_hi:[1,0]
	v_pk_mul_f32 v[4:5], v[4:5], v[130:131] op_sel_hi:[1,0]
	v_pk_mul_f32 v[2:3], v[2:3], v[130:131] op_sel_hi:[1,0]
	v_cvt_pk_bf16_f32 v98, v98, v99
	v_cvt_pk_bf16_f32 v99, v100, v101
	v_cvt_pk_bf16_f32 v100, v102, v103
	v_cvt_pk_bf16_f32 v101, v104, v105
	v_cvt_pk_bf16_f32 v102, v106, v107
	v_cvt_pk_bf16_f32 v103, v108, v109
	v_cvt_pk_bf16_f32 v104, v110, v111
	v_cvt_pk_bf16_f32 v105, v112, v113
	s_mulk_i32 s3, 0x4400
	v_mfma_f32_32x32x16_bf16 v[2:17], v[186:189], v[114:117], v[2:17]
	s_add_i32 s3, s3, 0
	s_add_i32 s3, s3, 0x1e800
	v_lshlrev_b32_e32 v106, 1, v163
	v_mul_lo_u32 v107, v162, s2
	v_add3_u32 v136, s3, v106, v107
	ds_read_b64_tr_b16 v[106:107], v144 offset:2048
	ds_read_b64_tr_b16 v[108:109], v131 offset:2048
	v_pk_mul_f32 v[32:33], v[32:33], v[130:131] op_sel_hi:[1,0]
	v_pk_mul_f32 v[30:31], v[30:31], v[130:131] op_sel_hi:[1,0]
	v_pk_mul_f32 v[28:29], v[28:29], v[130:131] op_sel_hi:[1,0]
	v_pk_mul_f32 v[26:27], v[26:27], v[130:131] op_sel_hi:[1,0]
	v_pk_mul_f32 v[24:25], v[24:25], v[130:131] op_sel_hi:[1,0]
	v_pk_mul_f32 v[22:23], v[22:23], v[130:131] op_sel_hi:[1,0]
	v_pk_mul_f32 v[20:21], v[20:21], v[130:131] op_sel_hi:[1,0]
	v_pk_mul_f32 v[18:19], v[18:19], v[130:131] op_sel_hi:[1,0]
	v_cvt_pk_bf16_f32 v82, v82, v83
	ds_write_b16 v136, v82
	ds_write_b16_d16_hi v136, v82 offset:272
	v_mfma_f32_32x32x16_bf16 v[2:17], v[132:135], v[118:121], v[2:17]
	ds_read_b64_tr_b16 v[110:111], v144 offset:2304
	ds_read_b64_tr_b16 v[112:113], v131 offset:2304
	v_cvt_pk_bf16_f32 v82, v84, v85
	ds_write_b16 v136, v82 offset:544
	ds_write_b16_d16_hi v136, v82 offset:816
	s_waitcnt lgkmcnt(10)
	v_mfma_f32_32x32x16_bf16 v[2:17], v[122:125], v[98:101], v[2:17]
	ds_read_b64_tr_b16 v[82:83], v144 offset:10240
	ds_read_b64_tr_b16 v[84:85], v131 offset:10240
	v_cvt_pk_bf16_f32 v86, v86, v87
	ds_write_b16 v136, v86 offset:2176
	ds_write_b16_d16_hi v136, v86 offset:2448
	s_waitcnt lgkmcnt(12)
	v_mfma_f32_32x32x16_bf16 v[2:17], v[126:129], v[102:105], v[2:17]
	ds_read_b64_tr_b16 v[122:123], v144 offset:10496
	ds_read_b64_tr_b16 v[124:125], v131 offset:10496
	v_cvt_pk_bf16_f32 v86, v88, v89
	ds_write_b16 v136, v86 offset:2720
	ds_write_b16_d16_hi v136, v86 offset:2992
	s_waitcnt lgkmcnt(14)
	v_mfma_f32_32x32x16_bf16 v[18:33], v[106:109], v[114:117], v[18:33]
	ds_read_b64_tr_b16 v[86:87], v144 offset:4096
	ds_read_b64_tr_b16 v[88:89], v131 offset:4096
	v_mul_f32_e64 v48, v48, v130
	v_mul_f32_e64 v49, v49, v130
	v_mul_f32_e64 v46, v46, v130
	v_mul_f32_e64 v47, v47, v130
	v_pk_mul_f32 v[44:45], v[44:45], v[130:131] op_sel_hi:[1,0]
	v_pk_mul_f32 v[42:43], v[42:43], v[130:131] op_sel_hi:[1,0]
	v_pk_mul_f32 v[40:41], v[40:41], v[130:131] op_sel_hi:[1,0]
	v_pk_mul_f32 v[38:39], v[38:39], v[130:131] op_sel_hi:[1,0]
	v_pk_mul_f32 v[36:37], v[36:37], v[130:131] op_sel_hi:[1,0]
	v_pk_mul_f32 v[34:35], v[34:35], v[130:131] op_sel_hi:[1,0]
	v_cvt_pk_bf16_f32 v90, v90, v91
	ds_write_b16 v136, v90 offset:4352
	ds_write_b16_d16_hi v136, v90 offset:4624
	s_waitcnt lgkmcnt(14)
	v_mfma_f32_32x32x16_bf16 v[18:33], v[110:113], v[118:121], v[18:33]
	ds_read_b64_tr_b16 v[106:107], v144 offset:4352
	ds_read_b64_tr_b16 v[108:109], v131 offset:4352
	v_cvt_pk_bf16_f32 v90, v92, v93
	ds_write_b16 v136, v90 offset:4896
	ds_write_b16_d16_hi v136, v90 offset:5168
	s_waitcnt lgkmcnt(14)
	v_mfma_f32_32x32x16_bf16 v[18:33], v[82:85], v[98:101], v[18:33]
	ds_read_b64_tr_b16 v[90:91], v144 offset:12288
	ds_read_b64_tr_b16 v[92:93], v131 offset:12288
	v_cvt_pk_bf16_f32 v94, v94, v95
	ds_write_b16 v136, v94 offset:6528
	ds_write_b16_d16_hi v136, v94 offset:6800
	s_waitcnt lgkmcnt(14)
	v_mfma_f32_32x32x16_bf16 v[18:33], v[122:125], v[102:105], v[18:33]
	ds_read_b64_tr_b16 v[82:83], v144 offset:12544
	ds_read_b64_tr_b16 v[84:85], v131 offset:12544
	v_cvt_pk_bf16_f32 v94, v96, v97
	ds_write_b16 v136, v94 offset:7072
	ds_write_b16_d16_hi v136, v94 offset:7344
	s_waitcnt lgkmcnt(14)
	v_mfma_f32_32x32x16_bf16 v[34:49], v[86:89], v[114:117], v[34:49]
	ds_read_b64_tr_b16 v[94:95], v144 offset:6144
	ds_read_b64_tr_b16 v[96:97], v131 offset:6144
	v_mul_f32_e64 v64, v64, v130
	v_mul_f32_e64 v65, v65, v130
	v_mul_f32_e64 v62, v62, v130
	v_mul_f32_e64 v63, v63, v130
	v_pk_mul_f32 v[60:61], v[60:61], v[130:131] op_sel_hi:[1,0]
	v_pk_mul_f32 v[58:59], v[58:59], v[130:131] op_sel_hi:[1,0]
	v_pk_mul_f32 v[56:57], v[56:57], v[130:131] op_sel_hi:[1,0]
	v_pk_mul_f32 v[54:55], v[54:55], v[130:131] op_sel_hi:[1,0]
	v_pk_mul_f32 v[52:53], v[52:53], v[130:131] op_sel_hi:[1,0]
	v_pk_mul_f32 v[50:51], v[50:51], v[130:131] op_sel_hi:[1,0]
	v_cvt_pk_bf16_f32 v66, v66, v67
	ds_write_b16 v136, v66 offset:8704
	ds_write_b16_d16_hi v136, v66 offset:8976
	s_waitcnt lgkmcnt(14)
	v_mfma_f32_32x32x16_bf16 v[34:49], v[106:109], v[118:121], v[34:49]
	ds_read_b64_tr_b16 v[86:87], v144 offset:6400
	ds_read_b64_tr_b16 v[88:89], v131 offset:6400
	v_cvt_pk_bf16_f32 v66, v68, v69
	ds_write_b16 v136, v66 offset:9248
	ds_write_b16_d16_hi v136, v66 offset:9520
	s_waitcnt lgkmcnt(14)
	v_mfma_f32_32x32x16_bf16 v[34:49], v[90:93], v[98:101], v[34:49]
	ds_read_b64_tr_b16 v[66:67], v144 offset:14336
	ds_read_b64_tr_b16 v[68:69], v131 offset:14336
	v_cvt_pk_bf16_f32 v70, v70, v71
	ds_write_b16 v136, v70 offset:10880
	ds_write_b16_d16_hi v136, v70 offset:11152
	s_waitcnt lgkmcnt(14)
	v_mfma_f32_32x32x16_bf16 v[34:49], v[82:85], v[102:105], v[34:49]
	ds_read_b64_tr_b16 v[90:91], v144 offset:14592
	ds_read_b64_tr_b16 v[92:93], v131 offset:14592
	v_cvt_pk_bf16_f32 v70, v72, v73
	ds_write_b16 v136, v70 offset:11424
	ds_write_b16_d16_hi v136, v70 offset:11696
	s_waitcnt lgkmcnt(14)
	v_mfma_f32_32x32x16_bf16 v[50:65], v[94:97], v[114:117], v[50:65]
	v_cvt_pk_bf16_f32 v70, v74, v75
	ds_write_b16 v136, v70 offset:13056
	ds_write_b16_d16_hi v136, v70 offset:13328
	s_waitcnt lgkmcnt(12)
	v_mfma_f32_32x32x16_bf16 v[50:65], v[86:89], v[118:121], v[50:65]
	v_cvt_pk_bf16_f32 v70, v76, v77
	ds_write_b16 v136, v70 offset:13600
	ds_write_b16_d16_hi v136, v70 offset:13872
	s_waitcnt lgkmcnt(10)
	v_mfma_f32_32x32x16_bf16 v[50:65], v[66:69], v[98:101], v[50:65]
	v_cvt_pk_bf16_f32 v70, v78, v79
	ds_write_b16 v136, v70 offset:15232
	ds_write_b16_d16_hi v136, v70 offset:15504
	s_waitcnt lgkmcnt(8)
	v_mfma_f32_32x32x16_bf16 v[50:65], v[90:93], v[102:105], v[50:65]
	v_cvt_pk_bf16_f32 v66, v80, v81
	ds_write_b16 v136, v66 offset:15776
	ds_write_b16_d16_hi v136, v66 offset:16048
	s_waitcnt lgkmcnt(0)
	s_barrier
	s_add_i32 s1, s1, 1
	s_cmp_eq_u32 s1, 64
	s_cbranch_scc0 .LBB0_775
	s_mov_b64 s[0:1], 0

.LBB0_827:
	v_lshrrev_b32_e32 v2, 2, v1
	v_lshl_or_b32 v18, s1, 4, v2
	s_ashr_i32 s1, s0, 31
	s_lshl_b64 s[0:1], s[0:1], 12
	v_ashrrev_i32_e32 v19, 31, v18
	v_lshl_add_u64 v[2:3], s[0:1], 0, v[18:19]
	v_readlane_b32 s0, v249, 43
	v_readlane_b32 s1, v249, 44
	s_mov_b32 s2, 0xa600
	v_mov_b64_e32 v[6:7], s[28:29]
	v_mov_b64_e32 v[4:5], s[0:1]
	v_mad_u64_u32 v[4:5], s[0:1], v2, s2, v[4:5]
	v_mad_i32_i24 v5, v3, s2, v5
	s_movk_i32 s2, 0x3000
	v_mad_u64_u32 v[6:7], s[0:1], v2, s2, v[6:7]
	v_and_b32_e32 v8, 3, v0
	v_mad_i32_i24 v7, v3, s2, v7
	s_lshl_b32 s0, s22, 8
	s_mov_b32 s1, 0
	v_lshl_add_u64 v[2:3], v[6:7], 0, s[0:1]
	v_lshl_add_u64 v[4:5], v[4:5], 0, s[0:1]
	v_lshlrev_b32_e32 v42, 6, v8
	v_mov_b32_e32 v43, 0
	v_lshl_add_u64 v[4:5], v[4:5], 0, v[42:43]
	s_mov_b64 s[2:3], 0x4000
	v_lshl_add_u64 v[2:3], v[2:3], 0, v[42:43]
	s_mov_b64 s[22:23], 0x1000
	s_movk_i32 s0, 0x110
	s_add_u32 s24, s70, 0x1200
	v_lshl_add_u64 v[44:45], v[4:5], 0, s[2:3]
	v_lshl_add_u64 v[34:35], v[2:3], 0, s[22:23]
	global_load_dwordx4 v[14:17], v[44:45], off
	global_load_dwordx4 v[10:13], v[44:45], off offset:16
	global_load_dwordx4 v[6:9], v[44:45], off offset:32
	global_load_dwordx4 v[2:5], v[44:45], off offset:48
	v_cmp_eq_u32_e64 s[18:19], 0, v1
	v_mul_lo_u32 v1, v18, s0
	s_addc_u32 s25, s71, 0
	s_add_i32 s0, 0, 0x1e800
	s_barrier
	s_mov_b32 s98, 2
	s_mov_b32 s99, 0
	s_lshl_b64 s[100:101], s[98:99], 15
	s_add_u32 s100, s100, 0x4000
	s_addc_u32 s101, s101, 0
	v_lshl_add_u64 v[200:201], v[38:39], 0, s[100:101]
	s_mov_b64 s[100:101], 0x1000
	s_add_i32 m0, s33, 0x4000
	s_nop 0
	global_load_lds_dwordx4 v[200:201], off sc1
	v_lshl_add_u64 v[200:201], v[200:201], 0, s[100:101]
	s_add_i32 m0, s33, 0x5000
	s_nop 0
	global_load_lds_dwordx4 v[200:201], off sc1
	v_lshl_add_u64 v[200:201], v[200:201], 0, s[100:101]
	s_add_i32 m0, s33, 0x6000
	s_nop 0
	global_load_lds_dwordx4 v[200:201], off sc1
	v_lshl_add_u64 v[200:201], v[200:201], 0, s[100:101]
	s_add_i32 m0, s33, 0x7000
	s_nop 0
	global_load_lds_dwordx4 v[200:201], off sc1
	s_mul_i32 s98, s98, 0x7400
	s_addk_i32 s98, 0x3000
	v_lshl_add_u64 v[202:203], v[40:41], 0, s[98:99]
	s_add_i32 m0, s33, 0xb000
	s_nop 0
	global_load_lds_dwordx4 v[202:203], off sc1
	v_lshl_add_u64 v[202:203], v[202:203], 0, s[100:101]
	s_add_i32 m0, s33, 0xc000
	s_nop 0
	global_load_lds_dwordx4 v[202:203], off sc1
	v_lshl_add_u64 v[202:203], v[202:203], 0, s[100:101]
	s_add_i32 m0, s33, 0xd000
	s_nop 0
	global_load_lds_dwordx4 v[202:203], off sc1
	v_lshl_add_u64 v[202:203], v[202:203], 0, s[100:101]
	s_add_i32 m0, s33, 0xe000
	s_nop 0
	global_load_lds_dwordx4 v[202:203], off sc1
	s_waitcnt vmcnt(8) lgkmcnt(0)
	s_barrier
	v_add_u32_e32 v18, s0, v1
	s_add_i32 s0, 0, 0x22c00
	s_mov_b32 s38, 2
	v_add_u32_e32 v1, s0, v1
	v_mbcnt_lo_u32_b32 v19, -1, 0
	s_mov_b32 s51, 1
	s_mov_b64 s[26:27], 0x2000
	s_mov_b64 s[28:29], 0x3000
	s_mov_b64 s[30:31], 0x5000
	s_mov_b64 s[34:35], 0x6000
	s_mov_b64 s[36:37], 0x7000
	s_add_i32 s50, s33, 0x8000
	s_add_i32 s52, s33, 0x9000
	s_add_i32 s53, s33, 0xa000
	s_add_i32 s54, s33, 0xb000
	s_add_i32 s55, s33, 0xc000
	s_add_i32 s56, s33, 0xd000
	s_add_i32 s57, s33, 0xe000
	s_add_i32 s58, s33, 0xf000
	v_mbcnt_hi_u32_b32 v48, -1, v19
	v_mov_b32_e32 v49, 0x358637bd
	s_mov_b32 s59, 0x800000
	s_mov_b32 s60, 0xfff40000
	s_mov_b32 s61, 0xfff41000
	v_mov_b32_e32 v50, 0x7400
	v_mov_b32_e32 v51, 0xa600
	v_add_u32_e32 v47, v18, v42
	v_mov_b32_e32 v52, 0x298000
	v_add_u32_e32 v1, v1, v42
	v_mov_b32_e32 v53, 0x3000
	s_mov_b32 s0, s38
	s_branch .LBB0_829
.LBB0_828:
	v_mad_u64_u32 v[54:55], s[62:63], s0, v52, v[44:45]
	global_load_dwordx4 v[14:17], v[54:55], off
	global_load_dwordx4 v[10:13], v[54:55], off offset:16
	global_load_dwordx4 v[6:9], v[54:55], off offset:32
	global_load_dwordx4 v[2:5], v[54:55], off offset:48
	s_barrier
	s_cmp_gt_u32 s51, 60
	s_cbranch_scc1 .Lscan_v2_nomid
	s_add_i32 s98, s51, 3
	s_mov_b32 s99, 0
	s_lshl_b64 s[100:101], s[98:99], 15
	s_add_u32 s100, s100, 0x4000
	s_addc_u32 s101, s101, 0
	v_lshl_add_u64 v[200:201], v[38:39], 0, s[100:101]
	s_mov_b64 s[100:101], 0x1000
	s_add_i32 m0, s33, 0x4000
	s_nop 0
	global_load_lds_dwordx4 v[200:201], off sc1
	v_lshl_add_u64 v[200:201], v[200:201], 0, s[100:101]
	s_add_i32 m0, s33, 0x5000
	s_nop 0
	global_load_lds_dwordx4 v[200:201], off sc1
	v_lshl_add_u64 v[200:201], v[200:201], 0, s[100:101]
	s_add_i32 m0, s33, 0x6000
	s_nop 0
	global_load_lds_dwordx4 v[200:201], off sc1
	v_lshl_add_u64 v[200:201], v[200:201], 0, s[100:101]
	s_add_i32 m0, s33, 0x7000
	s_nop 0
	global_load_lds_dwordx4 v[200:201], off sc1
	s_mul_i32 s98, s98, 0x7400
	s_addk_i32 s98, 0x3000
	v_lshl_add_u64 v[202:203], v[40:41], 0, s[98:99]
	s_add_i32 m0, s33, 0xb000
	s_nop 0
	global_load_lds_dwordx4 v[202:203], off sc1
	v_lshl_add_u64 v[202:203], v[202:203], 0, s[100:101]
	s_add_i32 m0, s33, 0xc000
	s_nop 0
	global_load_lds_dwordx4 v[202:203], off sc1
	v_lshl_add_u64 v[202:203], v[202:203], 0, s[100:101]
	s_add_i32 m0, s33, 0xd000
	s_nop 0
	global_load_lds_dwordx4 v[202:203], off sc1
	v_lshl_add_u64 v[202:203], v[202:203], 0, s[100:101]
	s_add_i32 m0, s33, 0xe000
	s_nop 0
	global_load_lds_dwordx4 v[202:203], off sc1
.Lscan_v2_nomid:
	s_setprio 0
	ds_read_b128 v[54:57], v1 offset:16
	ds_read_b128 v[58:61], v1
	ds_read_b128 v[62:65], v1 offset:32
	ds_read_b128 v[66:69], v1 offset:48
	v_lshlrev_b32_e32 v94, 16, v31
	s_waitcnt lgkmcnt(0)
	v_lshlrev_b32_e32 v71, 16, v55
	v_lshlrev_b32_e32 v70, 16, v54
	v_and_b32_e32 v55, 0xffff0000, v55
	v_and_b32_e32 v54, 0xffff0000, v54
	v_and_b32_e32 v89, 0xffff0000, v60
	v_and_b32_e32 v97, 0xffff0000, v58
	v_pk_mul_f32 v[72:73], v[54:55], v[54:55]
	v_lshlrev_b32_e32 v75, 16, v57
	v_lshlrev_b32_e32 v74, 16, v56
	v_and_b32_e32 v57, 0xffff0000, v57
	v_and_b32_e32 v56, 0xffff0000, v56
	v_lshlrev_b32_e32 v88, 16, v60
	v_and_b32_e32 v91, 0xffff0000, v59
	v_lshlrev_b32_e32 v96, 16, v58
	v_mov_b32_e32 v98, v89
	v_mov_b32_e32 v99, v97
	v_pk_fma_f32 v[72:73], v[70:71], v[70:71], v[72:73]
	v_pk_mul_f32 v[76:77], v[56:57], v[56:57]
	v_lshlrev_b32_e32 v84, 16, v61
	v_and_b32_e32 v85, 0xffff0000, v61
	v_lshlrev_b32_e32 v60, 16, v32
	v_and_b32_e32 v61, 0xffff0000, v32
	v_lshlrev_b32_e32 v90, 16, v59
	v_mul_f32_e32 v32, v91, v91
	v_mov_b32_e32 v58, v88
	v_mov_b32_e32 v59, v96
	v_pk_mul_f32 v[98:99], v[98:99], v[98:99]
	v_pk_add_f32 v[72:73], v[72:73], v[72:73] op_sel:[0,1] op_sel_hi:[1,0]
	v_pk_fma_f32 v[76:77], v[74:75], v[74:75], v[76:77]
	v_pk_fma_f32 v[92:93], v[90:91], v[90:91], v[32:33] op_sel_hi:[1,1,0]
	v_pk_fma_f32 v[58:59], v[58:59], v[58:59], v[98:99]
	v_pk_add_f32 v[72:73], v[76:77], v[72:73]
	v_mul_f32_e32 v86, v85, v85
	v_and_b32_e32 v95, 0xffff0000, v31
	v_lshlrev_b32_e32 v98, 16, v30
	v_and_b32_e32 v99, 0xffff0000, v30
	v_pk_add_f32 v[30:31], v[58:59], v[92:93] op_sel:[1,0] op_sel_hi:[0,1]
	v_pk_add_f32 v[72:73], v[76:77], v[72:73] op_sel:[1,0] op_sel_hi:[0,1]
	v_and_b32_e32 v77, 0xffff0000, v62
	v_pk_fma_f32 v[86:87], v[84:85], v[84:85], v[86:87] op_sel_hi:[1,1,0]
	v_pk_add_f32 v[30:31], v[58:59], v[30:31]
	v_lshlrev_b32_e32 v76, 16, v62
	v_mul_f32_e32 v62, v77, v77
	v_pk_mov_b32 v[100:101], v[64:65], v[68:69] op_sel:[1,0]
	v_lshlrev_b32_e32 v103, 16, v68
	v_lshlrev_b32_e32 v68, 16, v69
	v_and_b32_e32 v69, 0xffff0000, v69
	v_pk_add_f32 v[30:31], v[86:87], v[30:31]
	v_pk_fma_f32 v[78:79], v[76:77], v[76:77], v[62:63] op_sel_hi:[1,1,0]
	v_lshlrev_b32_e32 v62, 16, v63
	v_and_b32_e32 v63, 0xffff0000, v63
	v_mul_f32_e32 v73, v69, v69
	v_mul_f32_e32 v31, v68, v68
	v_mul_f32_e32 v80, v63, v63
	v_pk_add_f32 v[30:31], v[30:31], v[72:73]
	v_lshlrev_b32_e32 v72, 16, v67
	v_and_b32_e32 v73, 0xffff0000, v67
	v_pk_fma_f32 v[80:81], v[62:63], v[62:63], v[80:81] op_sel_hi:[1,1,0]
	v_and_b32_e32 v93, 0xffff0000, v66
	v_and_b32_e32 v92, 0xffff0000, v64
	v_pk_mul_f32 v[86:87], v[72:73], v[72:73]
	v_lshlrev_b32_e32 v59, 16, v66
	v_lshlrev_b32_e32 v58, 16, v64
	v_lshlrev_b32_e32 v102, 16, v65
	v_and_b32_e32 v65, 0xffff0000, v101
	v_and_b32_e32 v64, 0xffff0000, v100
	v_pk_mul_f32 v[100:101], v[92:93], v[92:93]
	v_mov_b32_e32 v79, v86
	v_mov_b32_e32 v81, v87
	v_pk_fma_f32 v[100:101], v[58:59], v[58:59], v[100:101]
	v_pk_mul_f32 v[104:105], v[64:65], v[64:65]
	v_pk_add_f32 v[78:79], v[78:79], v[80:81]
	v_pk_fma_f32 v[104:105], v[102:103], v[102:103], v[104:105]
	v_pk_add_f32 v[78:79], v[100:101], v[78:79]
	v_mov_b32_e32 v106, v70
	v_pk_add_f32 v[78:79], v[104:105], v[78:79]
	v_mov_b32_e32 v107, v54
	v_pk_add_f32 v[30:31], v[30:31], v[78:79]
	v_mov_b32_e32 v54, v71
	v_mov_b32_e32 v70, v74
	v_mov_b32_e32 v71, v56
	v_mov_b32_e32 v56, v75
	v_lshlrev_b32_e32 v74, 16, v22
	v_and_b32_e32 v75, 0xffff0000, v22
	v_add_f32_e32 v22, v30, v31
	ds_bpermute_b32 v79, v46, v22
	v_lshlrev_b32_e32 v66, 16, v23
	v_and_b32_e32 v67, 0xffff0000, v23
	v_lshlrev_b32_e32 v100, 16, v19
	v_and_b32_e32 v101, 0xffff0000, v19
	s_waitcnt lgkmcnt(0)
	v_add_f32_e32 v22, v22, v79
	ds_bpermute_b32 v23, v42, v22
	v_mov_b32_e32 v30, v58
	v_lshlrev_b32_e32 v78, 16, v24
	v_and_b32_e32 v79, 0xffff0000, v24
	v_lshlrev_b32_e32 v86, 16, v25
	s_waitcnt lgkmcnt(0)
	v_add_f32_e32 v22, v22, v23
	v_fmamk_f32 v22, v22, 0x3c000000, v49
	v_mul_f32_e32 v23, 0x4b800000, v22
	v_cmp_gt_f32_e32 vcc, s59, v22
	v_and_b32_e32 v87, 0xffff0000, v25
	v_lshlrev_b32_e32 v32, 16, v33
	v_cndmask_b32_e32 v22, v22, v23, vcc
	v_rsq_f32_e32 v22, v22
	v_and_b32_e32 v33, 0xffff0000, v33
	v_mad_u64_u32 v[82:83], s[40:41], s40, v53, v[34:35]
	v_mul_f32_e32 v19, 0x45800000, v22
	v_cndmask_b32_e32 v58, v22, v19, vcc
	v_pk_mul_f32 v[22:23], v[58:59], v[96:97] op_sel_hi:[0,1]
	v_pk_mul_f32 v[24:25], v[58:59], v[90:91] op_sel_hi:[0,1]
	v_pk_mul_f32 v[22:23], v[22:23], v[98:99]
	v_pk_mul_f32 v[24:25], v[24:25], v[94:95]
	v_cvt_pk_bf16_f32 v22, v22, v23
	v_cvt_pk_bf16_f32 v23, v24, v25
	v_pk_mul_f32 v[24:25], v[58:59], v[88:89] op_sel_hi:[0,1]
	v_pk_mul_f32 v[24:25], v[24:25], v[60:61]
	v_pk_mul_f32 v[60:61], v[58:59], v[84:85] op_sel_hi:[0,1]
	v_pk_mul_f32 v[32:33], v[60:61], v[32:33]
	v_cvt_pk_bf16_f32 v24, v24, v25
	v_cvt_pk_bf16_f32 v25, v32, v33
	v_lshlrev_b32_e32 v108, 16, v26
	v_and_b32_e32 v109, 0xffff0000, v26
	v_lshlrev_b32_e32 v26, 16, v27
	v_and_b32_e32 v27, 0xffff0000, v27
	global_store_dwordx4 v[82:83], v[22:25], off
	v_lshlrev_b32_e32 v110, 16, v28
	v_and_b32_e32 v111, 0xffff0000, v28
	v_pk_mul_f32 v[22:23], v[58:59], v[106:107] op_sel_hi:[0,1]
	v_pk_mul_f32 v[24:25], v[58:59], v[54:55] op_sel_hi:[0,1]
	v_pk_mul_f32 v[22:23], v[22:23], v[108:109]
	v_pk_mul_f32 v[24:25], v[24:25], v[26:27]
	v_lshlrev_b32_e32 v28, 16, v29
	v_and_b32_e32 v29, 0xffff0000, v29
	v_cvt_pk_bf16_f32 v22, v22, v23
	v_cvt_pk_bf16_f32 v23, v24, v25
	v_pk_mul_f32 v[24:25], v[58:59], v[70:71] op_sel_hi:[0,1]
	v_pk_mul_f32 v[26:27], v[58:59], v[56:57] op_sel_hi:[0,1]
	v_pk_mul_f32 v[24:25], v[24:25], v[110:111]
	v_pk_mul_f32 v[26:27], v[26:27], v[28:29]
	v_cvt_pk_bf16_f32 v24, v24, v25
	v_cvt_pk_bf16_f32 v25, v26, v27
	global_store_dwordx4 v[82:83], v[22:25], off offset:16
	v_mov_b32_e32 v31, v92
	v_mov_b32_e32 v80, v102
	v_pk_mul_f32 v[22:23], v[58:59], v[76:77] op_sel_hi:[0,1]
	v_pk_mul_f32 v[24:25], v[58:59], v[62:63] op_sel_hi:[0,1]
	v_mov_b32_e32 v81, v64
	v_pk_mul_f32 v[22:23], v[22:23], v[74:75]
	v_pk_mul_f32 v[24:25], v[24:25], v[66:67]
	v_cvt_pk_bf16_f32 v22, v22, v23
	v_cvt_pk_bf16_f32 v23, v24, v25
	v_pk_mul_f32 v[24:25], v[58:59], v[30:31] op_sel_hi:[0,1]
	v_pk_mul_f32 v[26:27], v[58:59], v[80:81] op_sel_hi:[0,1]
	v_pk_mul_f32 v[24:25], v[24:25], v[78:79]
	v_pk_mul_f32 v[26:27], v[26:27], v[86:87]
	v_cvt_pk_bf16_f32 v24, v24, v25
	v_cvt_pk_bf16_f32 v25, v26, v27
	v_mov_b32_e32 v92, v59
	global_store_dwordx4 v[82:83], v[22:25], off offset:32
	v_mov_b32_e32 v64, v103
	s_nop 0
	v_lshlrev_b32_e32 v22, 16, v18
	v_and_b32_e32 v23, 0xffff0000, v18
	v_pk_mul_f32 v[18:19], v[58:59], v[92:93] op_sel_hi:[0,1]
	v_pk_mul_f32 v[18:19], v[18:19], v[22:23]
	v_pk_mul_f32 v[22:23], v[58:59], v[72:73] op_sel_hi:[0,1]
	v_pk_mul_f32 v[22:23], v[22:23], v[100:101]
	v_cvt_pk_bf16_f32 v18, v18, v19
	v_cvt_pk_bf16_f32 v19, v22, v23
	v_lshlrev_b32_e32 v22, 16, v20
	v_and_b32_e32 v23, 0xffff0000, v20
	v_pk_mul_f32 v[24:25], v[58:59], v[64:65] op_sel_hi:[0,1]
	v_pk_mul_f32 v[22:23], v[24:25], v[22:23]
	v_lshlrev_b32_e32 v24, 16, v21
	v_cvt_pk_bf16_f32 v20, v22, v23
	v_pk_mul_f32 v[22:23], v[58:59], v[68:69] op_sel_hi:[0,1]
	v_and_b32_e32 v25, 0xffff0000, v21
	v_pk_mul_f32 v[22:23], v[22:23], v[24:25]
	s_nop 0
	v_cvt_pk_bf16_f32 v21, v22, v23
	global_store_dwordx4 v[82:83], v[18:21], off offset:48
	s_setprio 3
	s_cmp_gt_u32 s51, 60
	s_cbranch_scc1 .Lscan_v2_w4
	s_waitcnt vmcnt(12) lgkmcnt(0)
	s_branch .Lscan_v2_join
.Lscan_v2_w4:
	s_waitcnt vmcnt(4) lgkmcnt(0)
.Lscan_v2_join:
	s_barrier
	s_add_i32 s0, s51, 3
	s_cmp_gt_u32 s51, 60
	s_mov_b32 s51, s38
	s_cbranch_scc1 .LBB0_874

.LBB0_841:
.LBB0_842:
	s_lshl_b64 s[38:39], s[0:1], 15
	s_mov_b32 m0, s33
	v_lshl_add_u64 v[18:19], v[38:39], 0, s[38:39]
	global_load_lds_dwordx4 v[18:19], off sc1
	v_lshl_add_u64 v[20:21], v[18:19], 0, s[22:23]
	s_mov_b32 m0, s42
	s_and_b64 vcc, exec, s[20:21]
	global_load_lds_dwordx4 v[20:21], off sc1
	v_lshl_add_u64 v[20:21], v[18:19], 0, s[26:27]
	s_mov_b32 m0, s43
	s_nop 0
	global_load_lds_dwordx4 v[20:21], off sc1
	v_lshl_add_u64 v[20:21], v[18:19], 0, s[28:29]
	s_mov_b32 m0, s44
	s_nop 0
	global_load_lds_dwordx4 v[20:21], off sc1
	v_lshl_add_u64 v[20:21], v[18:19], 0, s[2:3]
	s_mov_b32 m0, s45
	s_nop 0
	v_lshl_add_u64 v[20:21], v[18:19], 0, s[30:31]
	s_mov_b32 m0, s46
	s_nop 0
	v_lshl_add_u64 v[20:21], v[18:19], 0, s[34:35]
	s_mov_b32 m0, s47
	v_lshl_add_u64 v[18:19], v[18:19], 0, s[36:37]
	s_mov_b32 m0, s48
	s_nop 0
	v_mad_u64_u32 v[18:19], s[38:39], s0, v50, v[40:41]
	s_cbranch_vccnz .LBB0_850
	s_mov_b32 m0, s50
	s_nop 0
	global_load_lds_dwordx4 v[18:19], off sc1
	s_and_b64 vcc, exec, s[4:5]
	s_cbranch_vccz .LBB0_851

.LBB0_847:
	v_lshl_add_u64 v[20:21], v[18:19], 0, s[2:3]
	s_mov_b32 m0, s55
	s_nop 0
	s_and_b64 vcc, exec, s[12:13]
	s_cbranch_vccz .LBB0_855

.LBB0_849:
	v_lshl_add_u64 v[20:21], v[18:19], 0, s[34:35]
	s_mov_b32 m0, s57
	s_nop 0
	s_and_b64 vcc, exec, s[16:17]
	s_cbranch_vccz .LBB0_857
	s_branch .LBB0_858

.LBB0_853:
	v_lshl_add_u64 v[20:21], v[18:19], 0, s[28:29]
	s_mov_b32 m0, s54
	s_nop 0
	s_and_b64 vcc, exec, s[10:11]
	s_cbranch_vccz .LBB0_847

.LBB0_855:
	v_lshl_add_u64 v[20:21], v[18:19], 0, s[30:31]
	s_mov_b32 m0, s56
	s_nop 0
	s_and_b64 vcc, exec, s[14:15]
	s_cbranch_vccz .LBB0_849

.LBB0_858:
	s_lshl_b32 s40, s51, 6
	v_mad_u64_u32 v[54:55], s[38:39], s40, v51, v[44:45]
	global_load_dwordx4 v[30:33], v[54:55], off
	global_load_dwordx4 v[26:29], v[54:55], off offset:16
	global_load_dwordx4 v[22:25], v[54:55], off offset:32
	global_load_dwordx4 v[18:21], v[54:55], off offset:48
	s_barrier
	s_add_i32 s98, s51, 2
	s_mov_b32 s99, 0
	s_lshl_b64 s[100:101], s[98:99], 15
	s_add_u32 s100, s100, 0x4000
	s_addc_u32 s101, s101, 0
	v_lshl_add_u64 v[200:201], v[38:39], 0, s[100:101]
	s_mov_b64 s[100:101], 0x1000
	s_add_i32 m0, s49, 0x4000
	s_nop 0
	global_load_lds_dwordx4 v[200:201], off sc1
	v_lshl_add_u64 v[200:201], v[200:201], 0, s[100:101]
	s_add_i32 m0, s49, 0x5000
	s_nop 0
	global_load_lds_dwordx4 v[200:201], off sc1
	v_lshl_add_u64 v[200:201], v[200:201], 0, s[100:101]
	s_add_i32 m0, s49, 0x6000
	s_nop 0
	global_load_lds_dwordx4 v[200:201], off sc1
	v_lshl_add_u64 v[200:201], v[200:201], 0, s[100:101]
	s_add_i32 m0, s49, 0x7000
	s_nop 0
	global_load_lds_dwordx4 v[200:201], off sc1
	s_mul_i32 s98, s98, 0x7400
	s_addk_i32 s98, 0x3000
	v_lshl_add_u64 v[202:203], v[40:41], 0, s[98:99]
	s_add_i32 m0, s49, 0xb000
	s_nop 0
	global_load_lds_dwordx4 v[202:203], off sc1
	v_lshl_add_u64 v[202:203], v[202:203], 0, s[100:101]
	s_add_i32 m0, s49, 0xc000
	s_nop 0
	global_load_lds_dwordx4 v[202:203], off sc1
	v_lshl_add_u64 v[202:203], v[202:203], 0, s[100:101]
	s_add_i32 m0, s49, 0xd000
	s_nop 0
	global_load_lds_dwordx4 v[202:203], off sc1
	v_lshl_add_u64 v[202:203], v[202:203], 0, s[100:101]
	s_add_i32 m0, s49, 0xe000
	s_nop 0
	global_load_lds_dwordx4 v[202:203], off sc1
	s_setprio 0
	ds_read_b128 v[54:57], v47 offset:16
	ds_read_b128 v[58:61], v47
	ds_read_b128 v[62:65], v47 offset:32
	ds_read_b128 v[66:69], v47 offset:48
	v_and_b32_e32 v46, 64, v48
	s_waitcnt lgkmcnt(0)
	v_lshlrev_b32_e32 v71, 16, v55
	v_lshlrev_b32_e32 v70, 16, v54
	v_and_b32_e32 v55, 0xffff0000, v55
	v_and_b32_e32 v54, 0xffff0000, v54
	v_pk_mul_f32 v[72:73], v[54:55], v[54:55]
	v_lshlrev_b32_e32 v75, 16, v57
	v_lshlrev_b32_e32 v74, 16, v56
	v_and_b32_e32 v57, 0xffff0000, v57
	v_and_b32_e32 v56, 0xffff0000, v56
	v_pk_fma_f32 v[72:73], v[70:71], v[70:71], v[72:73]
	v_pk_mul_f32 v[76:77], v[56:57], v[56:57]
	v_pk_add_f32 v[72:73], v[72:73], v[72:73] op_sel:[0,1] op_sel_hi:[1,0]
	v_pk_fma_f32 v[76:77], v[74:75], v[74:75], v[76:77]
	v_and_b32_e32 v89, 0xffff0000, v60
	v_pk_add_f32 v[72:73], v[76:77], v[72:73]
	v_and_b32_e32 v97, 0xffff0000, v58
	v_pk_add_f32 v[72:73], v[76:77], v[72:73] op_sel:[1,0] op_sel_hi:[0,1]
	v_and_b32_e32 v77, 0xffff0000, v62
	v_lshlrev_b32_e32 v76, 16, v62
	v_mul_f32_e32 v42, v77, v77
	v_lshlrev_b32_e32 v62, 16, v63
	v_and_b32_e32 v63, 0xffff0000, v63
	v_lshlrev_b32_e32 v88, 16, v60
	v_and_b32_e32 v91, 0xffff0000, v59
	v_lshlrev_b32_e32 v96, 16, v58
	v_mov_b32_e32 v98, v89
	v_mov_b32_e32 v99, v97
	v_pk_fma_f32 v[78:79], v[76:77], v[76:77], v[42:43] op_sel_hi:[1,1,0]
	v_mul_f32_e32 v42, v63, v63
	v_lshlrev_b32_e32 v84, 16, v61
	v_and_b32_e32 v85, 0xffff0000, v61
	v_lshlrev_b32_e32 v60, 16, v16
	v_and_b32_e32 v61, 0xffff0000, v16
	v_lshlrev_b32_e32 v90, 16, v59
	v_mul_f32_e32 v16, v91, v91
	v_mov_b32_e32 v58, v88
	v_mov_b32_e32 v59, v96
	v_pk_mul_f32 v[98:99], v[98:99], v[98:99]
	v_pk_fma_f32 v[80:81], v[62:63], v[62:63], v[42:43] op_sel_hi:[1,1,0]
	v_xor_b32_e32 v42, 1, v48
	v_add_u32_e32 v73, 64, v46
	v_pk_fma_f32 v[92:93], v[90:91], v[90:91], v[16:17] op_sel_hi:[1,1,0]
	v_pk_fma_f32 v[58:59], v[58:59], v[58:59], v[98:99]
	v_cmp_lt_i32_e32 vcc, v42, v73
	v_mul_f32_e32 v86, v85, v85
	v_lshlrev_b32_e32 v94, 16, v15
	v_and_b32_e32 v95, 0xffff0000, v15
	v_lshlrev_b32_e32 v98, 16, v14
	v_and_b32_e32 v99, 0xffff0000, v14
	v_pk_add_f32 v[14:15], v[58:59], v[92:93] op_sel:[1,0] op_sel_hi:[0,1]
	v_cndmask_b32_e32 v42, v48, v42, vcc
	v_pk_fma_f32 v[86:87], v[84:85], v[84:85], v[86:87] op_sel_hi:[1,1,0]
	v_pk_add_f32 v[14:15], v[58:59], v[14:15]
	v_lshlrev_b32_e32 v46, 2, v42
	v_xor_b32_e32 v42, 2, v48
	v_pk_mov_b32 v[100:101], v[64:65], v[68:69] op_sel:[1,0]
	v_lshlrev_b32_e32 v103, 16, v68
	v_lshlrev_b32_e32 v68, 16, v69
	v_and_b32_e32 v69, 0xffff0000, v69
	v_pk_add_f32 v[14:15], v[86:87], v[14:15]
	v_cmp_lt_i32_e32 vcc, v42, v73
	v_mul_f32_e32 v73, v69, v69
	v_mul_f32_e32 v15, v68, v68
	v_pk_add_f32 v[14:15], v[14:15], v[72:73]
	v_lshlrev_b32_e32 v72, 16, v67
	v_and_b32_e32 v73, 0xffff0000, v67
	v_and_b32_e32 v93, 0xffff0000, v66
	v_and_b32_e32 v92, 0xffff0000, v64
	v_pk_mul_f32 v[86:87], v[72:73], v[72:73]
	v_lshlrev_b32_e32 v59, 16, v66
	v_lshlrev_b32_e32 v58, 16, v64
	v_lshlrev_b32_e32 v102, 16, v65
	v_and_b32_e32 v65, 0xffff0000, v101
	v_and_b32_e32 v64, 0xffff0000, v100
	v_pk_mul_f32 v[100:101], v[92:93], v[92:93]
	v_mov_b32_e32 v79, v86
	v_mov_b32_e32 v81, v87
	v_pk_fma_f32 v[100:101], v[58:59], v[58:59], v[100:101]
	v_pk_mul_f32 v[104:105], v[64:65], v[64:65]
	v_pk_add_f32 v[78:79], v[78:79], v[80:81]
	v_pk_fma_f32 v[104:105], v[102:103], v[102:103], v[104:105]
	v_pk_add_f32 v[78:79], v[100:101], v[78:79]
	v_mov_b32_e32 v106, v70
	v_pk_add_f32 v[78:79], v[104:105], v[78:79]
	v_mov_b32_e32 v107, v54
	v_pk_add_f32 v[14:15], v[14:15], v[78:79]
	v_mov_b32_e32 v54, v71
	v_mov_b32_e32 v70, v74
	v_mov_b32_e32 v71, v56
	v_mov_b32_e32 v56, v75
	v_lshlrev_b32_e32 v74, 16, v6
	v_and_b32_e32 v75, 0xffff0000, v6
	v_add_f32_e32 v6, v14, v15
	ds_bpermute_b32 v79, v46, v6
	v_cndmask_b32_e32 v42, v48, v42, vcc
	v_lshlrev_b32_e32 v42, 2, v42
	v_lshlrev_b32_e32 v66, 16, v7
	v_and_b32_e32 v67, 0xffff0000, v7
	s_waitcnt lgkmcnt(0)
	v_add_f32_e32 v6, v6, v79
	ds_bpermute_b32 v7, v42, v6
	v_lshlrev_b32_e32 v100, 16, v3
	v_and_b32_e32 v101, 0xffff0000, v3
	v_mov_b32_e32 v14, v58
	v_lshlrev_b32_e32 v78, 16, v8
	s_waitcnt lgkmcnt(0)
	v_add_f32_e32 v6, v6, v7
	v_fmamk_f32 v6, v6, 0x3c000000, v49
	v_mul_f32_e32 v7, 0x4b800000, v6
	v_cmp_gt_f32_e32 vcc, s59, v6
	v_and_b32_e32 v79, 0xffff0000, v8
	v_lshlrev_b32_e32 v86, 16, v9
	v_cndmask_b32_e32 v6, v6, v7, vcc
	v_rsq_f32_e32 v6, v6
	v_and_b32_e32 v87, 0xffff0000, v9
	s_mul_i32 s38, s51, 0x60000
	s_mov_b32 s39, s1
	v_mul_f32_e32 v3, 0x45800000, v6
	v_cndmask_b32_e32 v58, v6, v3, vcc
	v_pk_mul_f32 v[6:7], v[58:59], v[96:97] op_sel_hi:[0,1]
	v_pk_mul_f32 v[8:9], v[58:59], v[90:91] op_sel_hi:[0,1]
	v_pk_mul_f32 v[6:7], v[6:7], v[98:99]
	v_pk_mul_f32 v[8:9], v[8:9], v[94:95]
	v_cvt_pk_bf16_f32 v6, v6, v7
	v_cvt_pk_bf16_f32 v7, v8, v9
	v_pk_mul_f32 v[8:9], v[58:59], v[88:89] op_sel_hi:[0,1]
	v_lshlrev_b32_e32 v16, 16, v17
	v_and_b32_e32 v17, 0xffff0000, v17
	v_pk_mul_f32 v[8:9], v[8:9], v[60:61]
	v_pk_mul_f32 v[60:61], v[58:59], v[84:85] op_sel_hi:[0,1]
	v_lshl_add_u64 v[82:83], s[38:39], 1, v[34:35]
	v_pk_mul_f32 v[16:17], v[60:61], v[16:17]
	v_cvt_pk_bf16_f32 v8, v8, v9
	v_cvt_pk_bf16_f32 v9, v16, v17
	v_add_co_u32_e32 v16, vcc, s60, v82
	v_lshlrev_b32_e32 v108, 16, v10
	s_nop 0
	v_addc_co_u32_e32 v17, vcc, -1, v83, vcc
	v_and_b32_e32 v109, 0xffff0000, v10
	v_lshlrev_b32_e32 v10, 16, v11
	v_and_b32_e32 v11, 0xffff0000, v11
	global_store_dwordx4 v[16:17], v[6:9], off
	v_lshlrev_b32_e32 v110, 16, v12
	v_and_b32_e32 v111, 0xffff0000, v12
	v_pk_mul_f32 v[6:7], v[58:59], v[106:107] op_sel_hi:[0,1]
	v_pk_mul_f32 v[8:9], v[58:59], v[54:55] op_sel_hi:[0,1]
	v_pk_mul_f32 v[6:7], v[6:7], v[108:109]
	v_pk_mul_f32 v[8:9], v[8:9], v[10:11]
	v_lshlrev_b32_e32 v12, 16, v13
	v_and_b32_e32 v13, 0xffff0000, v13
	v_cvt_pk_bf16_f32 v6, v6, v7
	v_cvt_pk_bf16_f32 v7, v8, v9
	v_pk_mul_f32 v[8:9], v[58:59], v[70:71] op_sel_hi:[0,1]
	v_pk_mul_f32 v[10:11], v[58:59], v[56:57] op_sel_hi:[0,1]
	v_pk_mul_f32 v[8:9], v[8:9], v[110:111]
	v_pk_mul_f32 v[10:11], v[10:11], v[12:13]
	v_cvt_pk_bf16_f32 v8, v8, v9
	v_cvt_pk_bf16_f32 v9, v10, v11
	v_add_co_u32_e32 v10, vcc, s61, v82
	v_mov_b32_e32 v15, v92
	s_nop 0
	v_addc_co_u32_e32 v11, vcc, -1, v83, vcc
	global_store_dwordx4 v[10:11], v[6:9], off offset:-4080
	v_mov_b32_e32 v80, v102
	v_mov_b32_e32 v81, v64
	v_pk_mul_f32 v[6:7], v[58:59], v[76:77] op_sel_hi:[0,1]
	v_pk_mul_f32 v[8:9], v[58:59], v[62:63] op_sel_hi:[0,1]
	v_pk_mul_f32 v[6:7], v[6:7], v[74:75]
	v_pk_mul_f32 v[8:9], v[8:9], v[66:67]
	v_cvt_pk_bf16_f32 v6, v6, v7
	v_cvt_pk_bf16_f32 v7, v8, v9
	v_pk_mul_f32 v[8:9], v[58:59], v[14:15] op_sel_hi:[0,1]
	v_pk_mul_f32 v[12:13], v[58:59], v[80:81] op_sel_hi:[0,1]
	v_pk_mul_f32 v[8:9], v[8:9], v[78:79]
	v_pk_mul_f32 v[12:13], v[12:13], v[86:87]
	v_cvt_pk_bf16_f32 v8, v8, v9
	v_cvt_pk_bf16_f32 v9, v12, v13
	v_mov_b32_e32 v92, v59
	global_store_dwordx4 v[10:11], v[6:9], off offset:-4064
	v_mov_b32_e32 v64, v103
	s_nop 0
	v_lshlrev_b32_e32 v6, 16, v2
	v_and_b32_e32 v7, 0xffff0000, v2
	v_pk_mul_f32 v[2:3], v[58:59], v[92:93] op_sel_hi:[0,1]
	v_pk_mul_f32 v[2:3], v[2:3], v[6:7]
	v_pk_mul_f32 v[6:7], v[58:59], v[72:73] op_sel_hi:[0,1]
	v_pk_mul_f32 v[6:7], v[6:7], v[100:101]
	v_cvt_pk_bf16_f32 v2, v2, v3
	v_cvt_pk_bf16_f32 v3, v6, v7
	v_lshlrev_b32_e32 v6, 16, v4
	v_and_b32_e32 v7, 0xffff0000, v4
	v_pk_mul_f32 v[8:9], v[58:59], v[64:65] op_sel_hi:[0,1]
	v_pk_mul_f32 v[6:7], v[8:9], v[6:7]
	v_lshlrev_b32_e32 v8, 16, v5
	v_cvt_pk_bf16_f32 v4, v6, v7
	v_pk_mul_f32 v[6:7], v[58:59], v[68:69] op_sel_hi:[0,1]
	v_and_b32_e32 v9, 0xffff0000, v5
	v_pk_mul_f32 v[6:7], v[6:7], v[8:9]
	s_nop 0
	v_cvt_pk_bf16_f32 v5, v6, v7
	global_store_dwordx4 v[10:11], v[2:5], off offset:-4048
	s_setprio 3
	s_add_i32 s38, s51, 2
	s_lshl_b64 s[62:63], s[38:39], 15
	s_mov_b32 m0, s49
	s_waitcnt vmcnt(12) lgkmcnt(0)
	s_barrier
	v_lshl_add_u64 v[2:3], v[38:39], 0, s[62:63]
	global_load_lds_dwordx4 v[2:3], off sc1
	v_lshl_add_u64 v[4:5], v[2:3], 0, s[22:23]
	s_add_i32 m0, s49, 0x1000
	s_and_b64 vcc, exec, s[20:21]
	global_load_lds_dwordx4 v[4:5], off sc1
	v_lshl_add_u64 v[4:5], v[2:3], 0, s[26:27]
	s_add_i32 m0, s49, 0x2000
	s_nop 0
	global_load_lds_dwordx4 v[4:5], off sc1
	v_lshl_add_u64 v[4:5], v[2:3], 0, s[28:29]
	s_add_i32 m0, s49, 0x3000
	s_nop 0
	global_load_lds_dwordx4 v[4:5], off sc1
	v_lshl_add_u64 v[4:5], v[2:3], 0, s[2:3]
	s_add_i32 m0, s49, 0x4000
	s_nop 0
	v_lshl_add_u64 v[4:5], v[2:3], 0, s[30:31]
	s_add_i32 m0, s49, 0x5000
	s_nop 0
	v_lshl_add_u64 v[4:5], v[2:3], 0, s[34:35]
	s_add_i32 m0, s49, 0x6000
	v_lshl_add_u64 v[2:3], v[2:3], 0, s[36:37]
	s_add_i32 m0, s49, 0x7000
	s_nop 0
	v_mad_u64_u32 v[2:3], s[62:63], s38, v50, v[40:41]
	s_cbranch_vccnz .LBB0_866
	s_add_i32 m0, s49, 0x8000
	s_nop 0
	global_load_lds_dwordx4 v[2:3], off sc1
	s_and_b64 vcc, exec, s[4:5]
	s_cbranch_vccz .LBB0_867

.LBB0_863:
	v_lshl_add_u64 v[4:5], v[2:3], 0, s[2:3]
	s_add_i32 m0, s49, 0xc000
	s_nop 0
	s_and_b64 vcc, exec, s[12:13]
	s_cbranch_vccz .LBB0_871

.LBB0_865:
	v_lshl_add_u64 v[4:5], v[2:3], 0, s[34:35]
	s_add_i32 m0, s49, 0xe000
	s_nop 0
	s_and_b64 vcc, exec, s[16:17]
	s_cbranch_vccnz .LBB0_828
	s_branch .LBB0_873

.LBB0_869:
	v_lshl_add_u64 v[4:5], v[2:3], 0, s[28:29]
	s_add_i32 m0, s49, 0xb000
	s_nop 0
	s_and_b64 vcc, exec, s[10:11]
	s_cbranch_vccz .LBB0_863

.LBB0_871:
	v_lshl_add_u64 v[4:5], v[2:3], 0, s[30:31]
	s_add_i32 m0, s49, 0xd000
	s_nop 0
	s_and_b64 vcc, exec, s[14:15]
	s_cbranch_vccz .LBB0_865

.LBB0_874:
	s_mov_b64 s[0:1], 0xa368000
	v_lshl_add_u64 v[36:37], v[44:45], 0, s[0:1]
	global_load_dwordx4 v[30:33], v[36:37], off
	global_load_dwordx4 v[26:29], v[36:37], off offset:16
	global_load_dwordx4 v[22:25], v[36:37], off offset:32
	global_load_dwordx4 v[18:21], v[36:37], off offset:48
	s_barrier
	s_setprio 0
	ds_read_b128 v[36:39], v47 offset:16
	ds_read_b128 v[48:51], v47
	ds_read_b128 v[52:55], v47 offset:32
	ds_read_b128 v[56:59], v47 offset:48
	v_lshlrev_b32_e32 v78, 16, v15
	s_waitcnt lgkmcnt(0)
	v_lshlrev_b32_e32 v41, 16, v37
	v_lshlrev_b32_e32 v40, 16, v36
	v_and_b32_e32 v37, 0xffff0000, v37
	v_and_b32_e32 v36, 0xffff0000, v36
	v_and_b32_e32 v73, 0xffff0000, v50
	v_and_b32_e32 v81, 0xffff0000, v48
	v_pk_mul_f32 v[44:45], v[36:37], v[36:37]
	v_lshlrev_b32_e32 v61, 16, v39
	v_lshlrev_b32_e32 v60, 16, v38
	v_and_b32_e32 v39, 0xffff0000, v39
	v_and_b32_e32 v38, 0xffff0000, v38
	v_lshlrev_b32_e32 v72, 16, v50
	v_and_b32_e32 v75, 0xffff0000, v49
	v_lshlrev_b32_e32 v80, 16, v48
	v_mov_b32_e32 v82, v73
	v_mov_b32_e32 v83, v81
	v_pk_fma_f32 v[44:45], v[40:41], v[40:41], v[44:45]
	v_pk_mul_f32 v[62:63], v[38:39], v[38:39]
	v_lshlrev_b32_e32 v68, 16, v51
	v_and_b32_e32 v69, 0xffff0000, v51
	v_lshlrev_b32_e32 v50, 16, v16
	v_and_b32_e32 v51, 0xffff0000, v16
	v_lshlrev_b32_e32 v74, 16, v49
	v_mul_f32_e32 v16, v75, v75
	v_mov_b32_e32 v48, v72
	v_mov_b32_e32 v49, v80
	v_pk_mul_f32 v[82:83], v[82:83], v[82:83]
	v_pk_add_f32 v[44:45], v[44:45], v[44:45] op_sel:[0,1] op_sel_hi:[1,0]
	v_pk_fma_f32 v[62:63], v[60:61], v[60:61], v[62:63]
	v_pk_fma_f32 v[76:77], v[74:75], v[74:75], v[16:17] op_sel_hi:[1,1,0]
	v_pk_fma_f32 v[48:49], v[48:49], v[48:49], v[82:83]
	v_pk_add_f32 v[44:45], v[62:63], v[44:45]
	v_mul_f32_e32 v70, v69, v69
	v_and_b32_e32 v79, 0xffff0000, v15
	v_lshlrev_b32_e32 v82, 16, v14
	v_and_b32_e32 v83, 0xffff0000, v14
	v_pk_add_f32 v[14:15], v[48:49], v[76:77] op_sel:[1,0] op_sel_hi:[0,1]
	v_pk_add_f32 v[44:45], v[62:63], v[44:45] op_sel:[1,0] op_sel_hi:[0,1]
	v_and_b32_e32 v63, 0xffff0000, v52
	v_pk_fma_f32 v[70:71], v[68:69], v[68:69], v[70:71] op_sel_hi:[1,1,0]
	v_pk_add_f32 v[14:15], v[48:49], v[14:15]
	v_lshlrev_b32_e32 v62, 16, v52
	v_mul_f32_e32 v52, v63, v63
	v_pk_mov_b32 v[84:85], v[54:55], v[58:59] op_sel:[1,0]
	v_lshlrev_b32_e32 v87, 16, v58
	v_lshlrev_b32_e32 v58, 16, v59
	v_and_b32_e32 v59, 0xffff0000, v59
	v_pk_add_f32 v[14:15], v[70:71], v[14:15]
	v_pk_fma_f32 v[64:65], v[62:63], v[62:63], v[52:53] op_sel_hi:[1,1,0]
	v_lshlrev_b32_e32 v52, 16, v53
	v_and_b32_e32 v53, 0xffff0000, v53
	v_mul_f32_e32 v45, v59, v59
	v_mul_f32_e32 v15, v58, v58
	v_mul_f32_e32 v66, v53, v53
	v_pk_add_f32 v[14:15], v[14:15], v[44:45]
	v_lshlrev_b32_e32 v44, 16, v57
	v_and_b32_e32 v45, 0xffff0000, v57
	v_pk_fma_f32 v[66:67], v[52:53], v[52:53], v[66:67] op_sel_hi:[1,1,0]
	v_and_b32_e32 v77, 0xffff0000, v56
	v_and_b32_e32 v76, 0xffff0000, v54
	v_pk_mul_f32 v[70:71], v[44:45], v[44:45]
	v_lshlrev_b32_e32 v49, 16, v56
	v_lshlrev_b32_e32 v48, 16, v54
	v_lshlrev_b32_e32 v86, 16, v55
	v_and_b32_e32 v55, 0xffff0000, v85
	v_and_b32_e32 v54, 0xffff0000, v84
	v_pk_mul_f32 v[84:85], v[76:77], v[76:77]
	v_mov_b32_e32 v65, v70
	v_mov_b32_e32 v67, v71
	v_pk_fma_f32 v[84:85], v[48:49], v[48:49], v[84:85]
	v_pk_mul_f32 v[88:89], v[54:55], v[54:55]
	v_pk_add_f32 v[64:65], v[64:65], v[66:67]
	v_pk_fma_f32 v[88:89], v[86:87], v[86:87], v[88:89]
	v_pk_add_f32 v[64:65], v[84:85], v[64:65]
	v_mov_b32_e32 v90, v40
	v_pk_add_f32 v[64:65], v[88:89], v[64:65]
	v_mov_b32_e32 v91, v36
	v_pk_add_f32 v[14:15], v[14:15], v[64:65]
	v_mov_b32_e32 v36, v41
	v_mov_b32_e32 v40, v60
	v_mov_b32_e32 v41, v38
	v_mov_b32_e32 v38, v61
	v_lshlrev_b32_e32 v60, 16, v6
	v_and_b32_e32 v61, 0xffff0000, v6
	v_add_f32_e32 v6, v14, v15
	ds_bpermute_b32 v43, v46, v6
	v_lshlrev_b32_e32 v56, 16, v7
	v_and_b32_e32 v57, 0xffff0000, v7
	v_mov_b32_e32 v66, v86
	v_mov_b32_e32 v86, 0x358637bd
	s_waitcnt lgkmcnt(0)
	v_add_f32_e32 v6, v6, v43
	ds_bpermute_b32 v7, v42, v6
	s_mov_b32 s0, 0x800000
	v_lshlrev_b32_e32 v84, 16, v3
	v_and_b32_e32 v85, 0xffff0000, v3
	v_mov_b32_e32 v14, v48
	s_waitcnt lgkmcnt(0)
	v_add_f32_e32 v6, v6, v7
	v_fmamk_f32 v6, v6, 0x3c000000, v86
	v_mul_f32_e32 v7, 0x4b800000, v6
	v_cmp_gt_f32_e32 vcc, s0, v6
	v_lshlrev_b32_e32 v64, 16, v8
	v_and_b32_e32 v65, 0xffff0000, v8
	v_cndmask_b32_e32 v6, v6, v7, vcc
	v_rsq_f32_e32 v6, v6
	v_lshlrev_b32_e32 v70, 16, v9
	v_and_b32_e32 v71, 0xffff0000, v9
	v_lshlrev_b32_e32 v16, 16, v17
	v_mul_f32_e32 v3, 0x45800000, v6
	v_cndmask_b32_e32 v48, v6, v3, vcc
	v_pk_mul_f32 v[6:7], v[48:49], v[80:81] op_sel_hi:[0,1]
	v_pk_mul_f32 v[8:9], v[48:49], v[74:75] op_sel_hi:[0,1]
	v_pk_mul_f32 v[6:7], v[6:7], v[82:83]
	v_pk_mul_f32 v[8:9], v[8:9], v[78:79]
	v_cvt_pk_bf16_f32 v6, v6, v7
	v_cvt_pk_bf16_f32 v7, v8, v9
	v_pk_mul_f32 v[8:9], v[48:49], v[72:73] op_sel_hi:[0,1]
	v_and_b32_e32 v17, 0xffff0000, v17
	v_pk_mul_f32 v[8:9], v[8:9], v[50:51]
	v_pk_mul_f32 v[50:51], v[48:49], v[68:69] op_sel_hi:[0,1]
	v_pk_mul_f32 v[16:17], v[50:51], v[16:17]
	s_mov_b32 s1, 0x2e80000
	v_cvt_pk_bf16_f32 v8, v8, v9
	v_cvt_pk_bf16_f32 v9, v16, v17
	v_add_co_u32_e32 v16, vcc, s1, v34
	v_lshlrev_b32_e32 v92, 16, v10
	s_nop 0
	v_addc_co_u32_e32 v17, vcc, 0, v35, vcc
	v_and_b32_e32 v93, 0xffff0000, v10
	v_lshlrev_b32_e32 v10, 16, v11
	v_and_b32_e32 v11, 0xffff0000, v11
	global_store_dwordx4 v[16:17], v[6:9], off
	v_lshlrev_b32_e32 v94, 16, v12
	v_and_b32_e32 v95, 0xffff0000, v12
	v_pk_mul_f32 v[6:7], v[48:49], v[90:91] op_sel_hi:[0,1]
	v_pk_mul_f32 v[8:9], v[48:49], v[36:37] op_sel_hi:[0,1]
	v_pk_mul_f32 v[6:7], v[6:7], v[92:93]
	v_pk_mul_f32 v[8:9], v[8:9], v[10:11]
	v_lshlrev_b32_e32 v12, 16, v13
	v_and_b32_e32 v13, 0xffff0000, v13
	v_cvt_pk_bf16_f32 v6, v6, v7
	v_cvt_pk_bf16_f32 v7, v8, v9
	v_pk_mul_f32 v[8:9], v[48:49], v[40:41] op_sel_hi:[0,1]
	v_pk_mul_f32 v[10:11], v[48:49], v[38:39] op_sel_hi:[0,1]
	v_pk_mul_f32 v[8:9], v[8:9], v[94:95]
	v_pk_mul_f32 v[10:11], v[10:11], v[12:13]
	v_cvt_pk_bf16_f32 v8, v8, v9
	v_cvt_pk_bf16_f32 v9, v10, v11
	global_store_dwordx4 v[16:17], v[6:9], off offset:16
	v_mov_b32_e32 v15, v76
	v_mov_b32_e32 v67, v54
	v_pk_mul_f32 v[6:7], v[48:49], v[62:63] op_sel_hi:[0,1]
	v_pk_mul_f32 v[8:9], v[48:49], v[52:53] op_sel_hi:[0,1]
	v_pk_mul_f32 v[6:7], v[6:7], v[60:61]
	v_pk_mul_f32 v[8:9], v[8:9], v[56:57]
	v_cvt_pk_bf16_f32 v6, v6, v7
	v_cvt_pk_bf16_f32 v7, v8, v9
	v_pk_mul_f32 v[8:9], v[48:49], v[14:15] op_sel_hi:[0,1]
	v_pk_mul_f32 v[10:11], v[48:49], v[66:67] op_sel_hi:[0,1]
	v_pk_mul_f32 v[8:9], v[8:9], v[64:65]
	v_pk_mul_f32 v[10:11], v[10:11], v[70:71]
	v_cvt_pk_bf16_f32 v8, v8, v9
	v_cvt_pk_bf16_f32 v9, v10, v11
	v_mov_b32_e32 v76, v49
	global_store_dwordx4 v[16:17], v[6:9], off offset:32
	v_mov_b32_e32 v54, v87
	s_nop 0
	v_lshlrev_b32_e32 v6, 16, v2
	v_and_b32_e32 v7, 0xffff0000, v2
	v_pk_mul_f32 v[2:3], v[48:49], v[76:77] op_sel_hi:[0,1]
	v_pk_mul_f32 v[2:3], v[2:3], v[6:7]
	v_pk_mul_f32 v[6:7], v[48:49], v[44:45] op_sel_hi:[0,1]
	v_pk_mul_f32 v[6:7], v[6:7], v[84:85]
	v_cvt_pk_bf16_f32 v2, v2, v3
	v_cvt_pk_bf16_f32 v3, v6, v7
	v_lshlrev_b32_e32 v6, 16, v4
	v_and_b32_e32 v7, 0xffff0000, v4
	v_pk_mul_f32 v[8:9], v[48:49], v[54:55] op_sel_hi:[0,1]
	v_pk_mul_f32 v[6:7], v[8:9], v[6:7]
	v_lshlrev_b32_e32 v8, 16, v5
	v_cvt_pk_bf16_f32 v4, v6, v7
	v_pk_mul_f32 v[6:7], v[48:49], v[58:59] op_sel_hi:[0,1]
	v_and_b32_e32 v9, 0xffff0000, v5
	v_pk_mul_f32 v[6:7], v[6:7], v[8:9]
	s_nop 0
	v_cvt_pk_bf16_f32 v5, v6, v7
	global_store_dwordx4 v[16:17], v[2:5], off offset:48
	s_setprio 3
	s_waitcnt vmcnt(4) lgkmcnt(0)
	s_barrier
	s_setprio 0
	ds_read_b128 v[2:5], v1 offset:16
	ds_read_b128 v[6:9], v1
	ds_read_b128 v[10:13], v1 offset:32
	ds_read_b128 v[14:17], v1 offset:48
	v_lshlrev_b32_e32 v62, 16, v31
	s_waitcnt lgkmcnt(0)
	v_and_b32_e32 v39, 0xffff0000, v3
	v_and_b32_e32 v57, 0xffff0000, v8
	v_and_b32_e32 v65, 0xffff0000, v6
	v_and_b32_e32 v38, 0xffff0000, v2
	v_lshlrev_b32_e32 v56, 16, v8
	v_and_b32_e32 v59, 0xffff0000, v7
	v_lshlrev_b32_e32 v64, 16, v6
	v_mov_b32_e32 v66, v57
	v_mov_b32_e32 v67, v65
	v_lshlrev_b32_e32 v37, 16, v3
	v_lshlrev_b32_e32 v36, 16, v2
	v_pk_mul_f32 v[2:3], v[38:39], v[38:39]
	v_and_b32_e32 v45, 0xffff0000, v5
	v_and_b32_e32 v44, 0xffff0000, v4
	v_lshlrev_b32_e32 v52, 16, v9
	v_and_b32_e32 v53, 0xffff0000, v9
	v_lshlrev_b32_e32 v8, 16, v32
	v_and_b32_e32 v9, 0xffff0000, v32
	v_lshlrev_b32_e32 v58, 16, v7
	v_mul_f32_e32 v32, v59, v59
	v_mov_b32_e32 v6, v56
	v_mov_b32_e32 v7, v64
	v_pk_mul_f32 v[66:67], v[66:67], v[66:67]
	v_pk_fma_f32 v[2:3], v[36:37], v[36:37], v[2:3]
	v_lshlrev_b32_e32 v41, 16, v5
	v_lshlrev_b32_e32 v40, 16, v4
	v_pk_mul_f32 v[4:5], v[44:45], v[44:45]
	v_pk_fma_f32 v[60:61], v[58:59], v[58:59], v[32:33] op_sel_hi:[1,1,0]
	v_pk_fma_f32 v[6:7], v[6:7], v[6:7], v[66:67]
	v_pk_add_f32 v[2:3], v[2:3], v[2:3] op_sel:[0,1] op_sel_hi:[1,0]
	v_pk_fma_f32 v[4:5], v[40:41], v[40:41], v[4:5]
	v_mul_f32_e32 v54, v53, v53
	v_and_b32_e32 v63, 0xffff0000, v31
	v_lshlrev_b32_e32 v66, 16, v30
	v_and_b32_e32 v67, 0xffff0000, v30
	v_pk_add_f32 v[30:31], v[6:7], v[60:61] op_sel:[1,0] op_sel_hi:[0,1]
	v_pk_add_f32 v[2:3], v[4:5], v[2:3]
	v_pk_fma_f32 v[54:55], v[52:53], v[52:53], v[54:55] op_sel_hi:[1,1,0]
	v_pk_add_f32 v[6:7], v[6:7], v[30:31]
	v_pk_add_f32 v[2:3], v[4:5], v[2:3] op_sel:[1,0] op_sel_hi:[0,1]
	v_pk_mov_b32 v[68:69], v[12:13], v[16:17] op_sel:[1,0]
	v_lshlrev_b32_e32 v71, 16, v16
	v_lshlrev_b32_e32 v16, 16, v17
	v_and_b32_e32 v17, 0xffff0000, v17
	v_pk_add_f32 v[6:7], v[54:55], v[6:7]
	v_lshlrev_b32_e32 v48, 16, v10
	v_and_b32_e32 v49, 0xffff0000, v10
	v_lshlrev_b32_e32 v10, 16, v11
	v_and_b32_e32 v11, 0xffff0000, v11
	v_mul_f32_e32 v3, v17, v17
	v_mul_f32_e32 v7, v16, v16
	v_mul_f32_e32 v4, v49, v49
	v_mul_f32_e32 v50, v11, v11
	v_pk_add_f32 v[2:3], v[6:7], v[2:3]
	v_lshlrev_b32_e32 v6, 16, v15
	v_and_b32_e32 v7, 0xffff0000, v15
	v_pk_fma_f32 v[4:5], v[48:49], v[48:49], v[4:5] op_sel_hi:[1,1,0]
	v_pk_fma_f32 v[50:51], v[10:11], v[10:11], v[50:51] op_sel_hi:[1,1,0]
	v_and_b32_e32 v61, 0xffff0000, v14
	v_and_b32_e32 v60, 0xffff0000, v12
	v_pk_mul_f32 v[54:55], v[6:7], v[6:7]
	v_lshlrev_b32_e32 v31, 16, v14
	v_lshlrev_b32_e32 v30, 16, v12
	v_lshlrev_b32_e32 v70, 16, v13
	v_and_b32_e32 v13, 0xffff0000, v69
	v_and_b32_e32 v12, 0xffff0000, v68
	v_pk_mul_f32 v[68:69], v[60:61], v[60:61]
	v_mov_b32_e32 v5, v54
	v_mov_b32_e32 v51, v55
	v_pk_fma_f32 v[68:69], v[30:31], v[30:31], v[68:69]
	v_pk_mul_f32 v[72:73], v[12:13], v[12:13]
	v_pk_add_f32 v[4:5], v[4:5], v[50:51]
	v_pk_fma_f32 v[72:73], v[70:71], v[70:71], v[72:73]
	v_pk_add_f32 v[4:5], v[68:69], v[4:5]
	v_mov_b32_e32 v74, v36
	v_pk_add_f32 v[4:5], v[72:73], v[4:5]
	v_mov_b32_e32 v75, v38
	v_pk_add_f32 v[2:3], v[2:3], v[4:5]
	v_mov_b32_e32 v38, v37
	v_add_f32_e32 v1, v2, v3
	ds_bpermute_b32 v2, v46, v1
	v_mov_b32_e32 v36, v40
	v_mov_b32_e32 v37, v44
	v_mov_b32_e32 v44, v41
	v_lshlrev_b32_e32 v40, 16, v22
	s_waitcnt lgkmcnt(0)
	v_add_f32_e32 v1, v1, v2
	ds_bpermute_b32 v2, v42, v1
	v_and_b32_e32 v41, 0xffff0000, v22
	v_mov_b32_e32 v22, v30
	v_lshlrev_b32_e32 v32, 16, v33
	v_and_b32_e32 v33, 0xffff0000, v33
	s_waitcnt lgkmcnt(0)
	v_add_f32_e32 v1, v1, v2
	v_fmac_f32_e32 v86, 0x3c000000, v1
	v_mul_f32_e32 v1, 0x4b800000, v86
	v_cmp_gt_f32_e32 vcc, s0, v86
	s_mov_b32 s0, 0x2f40000
	v_lshlrev_b32_e32 v76, 16, v26
	v_cndmask_b32_e32 v1, v86, v1, vcc
	v_rsq_f32_e32 v1, v1
	v_and_b32_e32 v77, 0xffff0000, v26
	v_lshlrev_b32_e32 v26, 16, v27
	v_and_b32_e32 v27, 0xffff0000, v27
	v_mul_f32_e32 v2, 0x45800000, v1
	v_cndmask_b32_e32 v30, v1, v2, vcc
	v_pk_mul_f32 v[2:3], v[30:31], v[64:65] op_sel_hi:[0,1]
	v_pk_mul_f32 v[4:5], v[30:31], v[58:59] op_sel_hi:[0,1]
	v_pk_mul_f32 v[2:3], v[2:3], v[66:67]
	v_pk_mul_f32 v[4:5], v[4:5], v[62:63]
	v_cvt_pk_bf16_f32 v2, v2, v3
	v_cvt_pk_bf16_f32 v3, v4, v5
	v_pk_mul_f32 v[4:5], v[30:31], v[56:57] op_sel_hi:[0,1]
	v_pk_mul_f32 v[4:5], v[4:5], v[8:9]
	v_pk_mul_f32 v[8:9], v[30:31], v[52:53] op_sel_hi:[0,1]
	v_pk_mul_f32 v[8:9], v[8:9], v[32:33]
	v_cvt_pk_bf16_f32 v4, v4, v5
	v_cvt_pk_bf16_f32 v5, v8, v9
	v_add_co_u32_e32 v8, vcc, s0, v34
	v_lshlrev_b32_e32 v78, 16, v28
	s_nop 0
	v_addc_co_u32_e32 v9, vcc, 0, v35, vcc
	global_store_dwordx4 v[8:9], v[2:5], off
	v_and_b32_e32 v79, 0xffff0000, v28
	v_lshlrev_b32_e32 v28, 16, v29
	v_pk_mul_f32 v[2:3], v[30:31], v[74:75] op_sel_hi:[0,1]
	v_pk_mul_f32 v[4:5], v[30:31], v[38:39] op_sel_hi:[0,1]
	v_pk_mul_f32 v[2:3], v[2:3], v[76:77]
	v_pk_mul_f32 v[4:5], v[4:5], v[26:27]
	v_and_b32_e32 v29, 0xffff0000, v29
	v_cvt_pk_bf16_f32 v2, v2, v3
	v_cvt_pk_bf16_f32 v3, v4, v5
	v_pk_mul_f32 v[4:5], v[30:31], v[36:37] op_sel_hi:[0,1]
	v_pk_mul_f32 v[26:27], v[30:31], v[44:45] op_sel_hi:[0,1]
	v_pk_mul_f32 v[4:5], v[4:5], v[78:79]
	v_pk_mul_f32 v[26:27], v[26:27], v[28:29]
	v_cvt_pk_bf16_f32 v4, v4, v5
	v_cvt_pk_bf16_f32 v5, v26, v27
	v_lshlrev_b32_e32 v14, 16, v23
	v_and_b32_e32 v15, 0xffff0000, v23
	global_store_dwordx4 v[8:9], v[2:5], off offset:16
	v_mov_b32_e32 v23, v60
	v_mov_b32_e32 v42, v70
	v_pk_mul_f32 v[2:3], v[30:31], v[48:49] op_sel_hi:[0,1]
	v_pk_mul_f32 v[4:5], v[30:31], v[10:11] op_sel_hi:[0,1]
	v_mov_b32_e32 v43, v12
	v_pk_mul_f32 v[2:3], v[2:3], v[40:41]
	v_pk_mul_f32 v[4:5], v[4:5], v[14:15]
	v_lshlrev_b32_e32 v46, 16, v24
	v_and_b32_e32 v47, 0xffff0000, v24
	v_lshlrev_b32_e32 v24, 16, v25
	v_and_b32_e32 v25, 0xffff0000, v25
	v_cvt_pk_bf16_f32 v2, v2, v3
	v_cvt_pk_bf16_f32 v3, v4, v5
	v_pk_mul_f32 v[4:5], v[30:31], v[22:23] op_sel_hi:[0,1]
	v_pk_mul_f32 v[10:11], v[30:31], v[42:43] op_sel_hi:[0,1]
	v_pk_mul_f32 v[4:5], v[4:5], v[46:47]
	v_pk_mul_f32 v[10:11], v[10:11], v[24:25]
	v_cvt_pk_bf16_f32 v4, v4, v5
	v_cvt_pk_bf16_f32 v5, v10, v11
	v_mov_b32_e32 v60, v31
	global_store_dwordx4 v[8:9], v[2:5], off offset:32
	v_lshlrev_b32_e32 v50, 16, v19
	v_and_b32_e32 v51, 0xffff0000, v19
	v_lshlrev_b32_e32 v2, 16, v18
	v_and_b32_e32 v3, 0xffff0000, v18
	v_pk_mul_f32 v[4:5], v[30:31], v[60:61] op_sel_hi:[0,1]
	v_pk_mul_f32 v[2:3], v[4:5], v[2:3]
	v_pk_mul_f32 v[4:5], v[30:31], v[6:7] op_sel_hi:[0,1]
	v_pk_mul_f32 v[4:5], v[4:5], v[50:51]
	v_mov_b32_e32 v12, v71
	v_cvt_pk_bf16_f32 v2, v2, v3
	v_cvt_pk_bf16_f32 v3, v4, v5
	v_lshlrev_b32_e32 v4, 16, v20
	v_and_b32_e32 v5, 0xffff0000, v20
	v_pk_mul_f32 v[6:7], v[30:31], v[12:13] op_sel_hi:[0,1]
	v_pk_mul_f32 v[4:5], v[6:7], v[4:5]
	v_pk_mul_f32 v[6:7], v[30:31], v[16:17] op_sel_hi:[0,1]
	v_lshlrev_b32_e32 v10, 16, v21
	v_and_b32_e32 v11, 0xffff0000, v21
	v_pk_mul_f32 v[6:7], v[6:7], v[10:11]
	v_cvt_pk_bf16_f32 v4, v4, v5
	v_cvt_pk_bf16_f32 v5, v6, v7
	global_store_dwordx4 v[8:9], v[2:5], off offset:48
	s_setprio 3
	s_setprio 0
